# conv bias/LN params prefetched before tap loop; P16 loads hoisted to conv post start, P16 internal waits removed
# speedup vs baseline: 1.0031x; 1.0008x over previous
; #define LAS __attribute__((address_space(3)))
; __global__ void __launch_bounds__(NWAVES * 64, 2) fwd_kernel(Args args) {
;     ...
;                 { u32x4 wv[4], uv[12];
;                   if (first) {
; #pragma unroll
;                       for (int q = 0; q < 4; ++q) wv[q] = *((const u32x4*)CW16 + tid + 512 * q);
;                   }
; #pragma unroll
;                   for (int q = 0; q < 12; ++q) { const int i = tid + 512 * q; const int rr = i >> 6, ch = i & 63;
;                       const bool ok = i < 94 * 64 && tb - 30 + rr >= 0;
;                       const u32x4 ld = *(const u32x4*)(Ub + (ok ? (size_t)(t0 - 30 + rr) * CONV_CH + ch * 8 : (size_t)0));
;                       uv[q] = ok ? ld : (u32x4){0u, 0u, 0u, 0u}; }
;                   __syncthreads();
;                   if (first) {
; #pragma unroll
;                       for (int q = 0; q < 4; ++q) *((LAS u32x4*)wt + tid + 512 * q) = wv[q];
;                       ut[94 * CONV_CH + tid] = (f16_t)0.f;
;                   }
; #pragma unroll
;                   for (int q = 0; q < 12; ++q) { const int i = tid + 512 * q; if (i < 94 * 64) *((LAS u32x4*)ut + i) = uv[q]; } }
;                 first = false;
;                 __syncthreads();
;                 float acc[8][8];
; #pragma unroll
;                 for (int i = 0; i < 8; ++i)
; #pragma unroll
;                     for (int e = 0; e < 8; ++e) acc[i][e] = 0.f;
;                 const LAS f16_t* ub = ut + (wave * 8) * CONV_CH + c0;
;                 const LAS f16_t* wb = wt + c0;
;                 f16x8 win[15];
; #pragma unroll
;                 for (int i = 0; i < 7; ++i) win[8 + i] = *(const LAS f16x8*)(ub + i * CONV_CH);
; #pragma unroll 1
;                 for (int jj = 0; jj < 32; jj += 8) {
; #pragma unroll
;                     for (int i = 0; i < 7; ++i) win[i] = win[8 + i];
; #pragma unroll
;                     for (int i = 0; i < 8; ++i) win[7 + i] = *(const LAS f16x8*)(ub + (jj + 7 + i) * CONV_CH);
.LBB0_643:
	s_waitcnt vmcnt(6)
	ds_write_b128 v201, v[22:25]
	ds_write_b128 v201, v[18:21] offset:8192
	ds_write_b128 v201, v[30:33] offset:16384
	ds_write_b128 v201, v[26:29] offset:24576
	s_waitcnt vmcnt(5)
	ds_write_b128 v201, v[34:37] offset:32768
	s_waitcnt vmcnt(4)
	ds_write_b128 v201, v[38:41] offset:40960
	s_waitcnt vmcnt(3)
	ds_write_b128 v201, v[46:49] offset:49152
	s_waitcnt vmcnt(2)
	ds_write_b128 v201, v[50:53] offset:57344
	s_waitcnt vmcnt(1)
	ds_write_b128 v202, v[58:61]
	s_waitcnt vmcnt(0)
	v_lshl_add_u32 v249, s85, 9, v0
	v_lshlrev_b32_e32 v249, 5, v249
	global_load_dword v250, v249, s[38:39]
	s_add_u32 s98, s38, 0x400000
	s_addc_u32 s99, s39, 0
	global_load_dword v251, v249, s[98:99]
	s_add_u32 s98, s38, 0x800000
	s_addc_u32 s99, s39, 0
	global_load_dword v252, v249, s[98:99]
	s_add_u32 s98, s38, 0xc00000
	s_addc_u32 s99, s39, 0
	global_load_dword v253, v249, s[98:99]
	ds_write_b128 v203, v[62:65]
	s_and_saveexec_b64 s[0:1], s[2:3]
	ds_write_b128 v204, v[54:57]
	s_or_b64 exec, exec, s[0:1]
	s_and_saveexec_b64 s[0:1], s[4:5]
	ds_write_b128 v205, v[42:45]
	s_or_b64 exec, exec, s[0:1]
	s_waitcnt lgkmcnt(0)
	s_barrier
	global_load_dwordx4 v[2:5], v[116:117], off offset:16
	global_load_dwordx4 v[6:9], v[116:117], off
	global_load_dwordx4 v[10:13], v[106:107], off offset:16
	global_load_dwordx4 v[14:17], v[106:107], off
	global_load_dwordx4 v[250:253], v[114:115], off offset:16
	global_load_dwordx4 v[108:111], v[114:115], off
	ds_read_b128 v[42:45], v206
	ds_read_b128 v[38:41], v206 offset:1024
	ds_read_b128 v[30:33], v206 offset:2048
	ds_read_b128 v[18:21], v206 offset:3072
	ds_read_b128 v[22:25], v206 offset:4096
	ds_read_b128 v[26:29], v206 offset:5120
	ds_read_b128 v[34:37], v206 offset:6144
	v_mov_b32_e32 v174, 0
	s_mov_b32 s0, -8
	v_mov_b32_e32 v208, v98
	v_mov_b32_e32 v175, v174
	v_mov_b32_e32 v176, v174
	v_mov_b32_e32 v177, v174
	v_mov_b32_e32 v178, v174
	v_mov_b32_e32 v179, v174
	v_mov_b32_e32 v180, v174
	v_mov_b32_e32 v181, v174
	v_mov_b32_e32 v166, v174
	v_mov_b32_e32 v167, v174
	v_mov_b32_e32 v168, v174
	v_mov_b32_e32 v169, v174
	v_mov_b32_e32 v170, v174
	v_mov_b32_e32 v171, v174
	v_mov_b32_e32 v172, v174
	v_mov_b32_e32 v173, v174
	v_mov_b32_e32 v164, v174
	v_mov_b32_e32 v165, v174
	v_mov_b32_e32 v162, v174
	v_mov_b32_e32 v163, v174
	v_mov_b32_e32 v160, v174
	v_mov_b32_e32 v161, v174
	v_mov_b32_e32 v158, v174
	v_mov_b32_e32 v159, v174
	v_mov_b32_e32 v150, v174
	v_mov_b32_e32 v151, v174
	v_mov_b32_e32 v152, v174
	v_mov_b32_e32 v153, v174
	v_mov_b32_e32 v154, v174
	v_mov_b32_e32 v155, v174
	v_mov_b32_e32 v156, v174
	v_mov_b32_e32 v157, v174
	v_mov_b32_e32 v142, v174
	v_mov_b32_e32 v143, v174
	v_mov_b32_e32 v144, v174
	v_mov_b32_e32 v145, v174
	v_mov_b32_e32 v146, v174
	v_mov_b32_e32 v147, v174
	v_mov_b32_e32 v148, v174
	v_mov_b32_e32 v149, v174
	v_mov_b32_e32 v134, v174
	v_mov_b32_e32 v135, v174
	v_mov_b32_e32 v136, v174
	v_mov_b32_e32 v137, v174
	v_mov_b32_e32 v138, v174
	v_mov_b32_e32 v139, v174
	v_mov_b32_e32 v140, v174
	v_mov_b32_e32 v141, v174
	v_mov_b32_e32 v126, v174
	v_mov_b32_e32 v127, v174
	v_mov_b32_e32 v128, v174
	v_mov_b32_e32 v129, v174
	v_mov_b32_e32 v130, v174
	v_mov_b32_e32 v131, v174
	v_mov_b32_e32 v132, v174
	v_mov_b32_e32 v133, v174
	v_mov_b32_e32 v118, v174
	v_mov_b32_e32 v119, v174
	v_mov_b32_e32 v120, v174
	v_mov_b32_e32 v121, v174
	v_mov_b32_e32 v122, v174
	v_mov_b32_e32 v123, v174
	v_mov_b32_e32 v124, v174
	v_mov_b32_e32 v125, v174
.LBB0_648:
	v_add_u32_e32 v78, s7, v208
	ds_read_b128 v[74:77], v208
	ds_read_b128 v[50:53], v208 offset:1024
	ds_read_b128 v[54:57], v208 offset:2048
	ds_read_b128 v[58:61], v208 offset:3072
	ds_read_b128 v[62:65], v208 offset:4096
	ds_read_b128 v[66:69], v208 offset:5120
	ds_read_b128 v[70:73], v208 offset:6144
	ds_read_b128 v[46:49], v208 offset:7168
	v_add_u32_e32 v79, 0xfffe8400, v78
	v_add_u32_e32 v80, 0xfffe8800, v78
	v_add_u32_e32 v81, 0xfffe8c00, v78
	v_add_u32_e32 v82, 0xfffe9000, v78
	v_add_u32_e32 v83, 0xfffe9400, v78
	v_add_u32_e32 v84, 0xfffe9800, v78
	v_add_u32_e32 v85, 0xfffe9c00, v78
	v_add_u32_e32 v78, 0xfffea000, v78
	s_waitcnt lgkmcnt(7)
	v_pk_mul_f16 v42, v74, v42
	v_pk_mul_f16 v43, v75, v43
	v_pk_mul_f16 v44, v76, v44
	v_pk_mul_f16 v45, v77, v45
	v_pk_mul_f16 v209, v74, v38
	v_pk_mul_f16 v222, v75, v39
	v_pk_mul_f16 v223, v76, v40
	v_pk_mul_f16 v224, v77, v41
	v_pk_mul_f16 v225, v74, v30
	v_pk_mul_f16 v226, v75, v31
	v_pk_mul_f16 v227, v76, v32
	v_pk_mul_f16 v228, v77, v33
	v_pk_mul_f16 v229, v74, v18
	v_pk_mul_f16 v230, v75, v19
	v_pk_mul_f16 v232, v77, v21
	v_pk_mul_f16 v233, v74, v22
	v_pk_mul_f16 v236, v77, v25
	v_pk_mul_f16 v237, v74, v26
	v_pk_mul_f16 v240, v77, v29
	ds_read_b128 v[210:213], v79
	ds_read_b128 v[214:217], v80
	ds_read_b128 v[218:221], v81
	ds_read_b128 v[94:97], v82
	ds_read_b128 v[90:93], v83
	ds_read_b128 v[86:89], v84
	ds_read_b128 v[82:85], v85
	ds_read_b128 v[78:81], v78
	v_pk_mul_f16 v231, v76, v20
	v_pk_mul_f16 v234, v75, v23
	v_pk_mul_f16 v235, v76, v24
	v_pk_mul_f16 v238, v75, v27
	v_pk_mul_f16 v239, v76, v28
	v_pk_mul_f16 v241, v74, v34
	v_pk_mul_f16 v242, v75, v35
	v_pk_mul_f16 v243, v76, v36
	v_pk_mul_f16 v244, v77, v37
	s_waitcnt lgkmcnt(14)
	v_pk_fma_f16 v41, v53, v41, v45
	v_pk_fma_f16 v40, v52, v40, v44
	v_pk_fma_f16 v39, v51, v39, v43
	v_pk_fma_f16 v38, v50, v38, v42
	v_pk_fma_f16 v42, v53, v33, v224
	v_pk_fma_f16 v43, v52, v32, v223
	v_pk_fma_f16 v44, v51, v31, v222
	v_pk_fma_f16 v45, v50, v30, v209
	v_pk_fma_f16 v209, v53, v21, v228
	v_pk_fma_f16 v222, v52, v20, v227
	v_pk_fma_f16 v223, v51, v19, v226
	v_pk_fma_f16 v224, v50, v18, v225
	v_pk_fma_f16 v225, v53, v25, v232
	v_pk_fma_f16 v227, v51, v23, v230
	v_pk_fma_f16 v228, v50, v22, v229
	v_pk_fma_f16 v229, v53, v29, v236
	v_pk_fma_f16 v232, v50, v26, v233
	v_pk_fma_f16 v233, v53, v37, v240
	v_pk_fma_f16 v236, v50, v34, v237
	s_waitcnt lgkmcnt(7)
; #define LAS __attribute__((address_space(3)))
; __global__ void __launch_bounds__(NWAVES * 64, 2) fwd_kernel(Args args) {
;     ...
;                 for (int jj = 0; jj < 32; jj += 8) {
; #pragma unroll
;                     for (int i = 0; i < 7; ++i) win[i] = win[8 + i];
; #pragma unroll
;                     for (int i = 0; i < 8; ++i) win[7 + i] = *(const LAS f16x8*)(ub + (jj + 7 + i) * CONV_CH);
;                     f16x8 part[8];
; #pragma unroll
;                     for (int dj = 0; dj < 8; ++dj) {
;                         const f16x8 wj = *(const LAS f16x8*)(wb + (jj + dj) * CONV_CH);
; #pragma unroll
;                         for (int i = 0; i < 8; ++i) part[i] = (dj == 0) ? wj * win[i] : __builtin_elementwise_fma(wj, win[dj + i], part[i]);
;                     }
; #pragma unroll
;                     for (int i = 0; i < 8; ++i)
; #pragma unroll
;                         for (int e = 0; e < 8; ++e) acc[i][e] += (float)part[i][e];
;                 }
	v_pk_mul_f16 v74, v74, v210
	v_pk_mul_f16 v75, v75, v211
	v_pk_mul_f16 v76, v76, v212
	v_pk_mul_f16 v77, v77, v213
	v_pk_fma_f16 v226, v52, v24, v231
	v_pk_fma_f16 v230, v52, v28, v235
	v_pk_fma_f16 v231, v51, v27, v234
	v_pk_fma_f16 v234, v52, v36, v239
	v_pk_fma_f16 v235, v51, v35, v238
	v_pk_fma_f16 v237, v53, v213, v244
	v_pk_fma_f16 v238, v52, v212, v243
	v_pk_fma_f16 v239, v51, v211, v242
	v_pk_fma_f16 v240, v50, v210, v241
	v_pk_fma_f16 v241, v54, v30, v38
	v_pk_fma_f16 v242, v55, v31, v39
	v_pk_fma_f16 v243, v56, v32, v40
	v_pk_fma_f16 v244, v57, v33, v41
	v_pk_fma_f16 v245, v54, v18, v45
	v_pk_fma_f16 v246, v55, v19, v44
	v_pk_fma_f16 v247, v56, v20, v43
	v_pk_fma_f16 v248, v57, v21, v42
	v_pk_fma_f16 v224, v54, v22, v224
	v_pk_fma_f16 v223, v55, v23, v223
	v_pk_fma_f16 v222, v56, v24, v222
	v_pk_fma_f16 v209, v57, v25, v209
	v_pk_fma_f16 v228, v54, v26, v228
	v_pk_fma_f16 v227, v55, v27, v227
	v_pk_fma_f16 v225, v57, v29, v225
	v_pk_fma_f16 v232, v54, v34, v232
	v_pk_fma_f16 v229, v57, v37, v229
	v_pk_fma_f16 v236, v54, v210, v236
	v_pk_fma_f16 v233, v57, v213, v233
	s_waitcnt lgkmcnt(6)
	v_pk_fma_f16 v53, v53, v217, v77
	v_pk_fma_f16 v52, v52, v216, v76
	v_pk_fma_f16 v51, v51, v215, v75
	v_pk_fma_f16 v50, v50, v214, v74
	v_pk_fma_f16 v226, v56, v28, v226
	v_pk_fma_f16 v231, v55, v35, v231
	v_pk_fma_f16 v230, v56, v36, v230
	v_pk_fma_f16 v235, v55, v211, v235
	v_pk_fma_f16 v234, v56, v212, v234
	v_pk_fma_f16 v74, v54, v214, v240
	v_pk_fma_f16 v75, v55, v215, v239
	v_pk_fma_f16 v76, v56, v216, v238
	v_pk_fma_f16 v77, v57, v217, v237
	v_pk_fma_f16 v237, v61, v21, v244
	v_pk_fma_f16 v238, v60, v20, v243
	v_pk_fma_f16 v239, v59, v19, v242
	v_pk_fma_f16 v240, v58, v18, v241
	v_pk_fma_f16 v241, v61, v25, v248
	v_pk_fma_f16 v242, v60, v24, v247
	v_pk_fma_f16 v243, v59, v23, v246
	v_pk_fma_f16 v244, v58, v22, v245
	v_pk_fma_f16 v209, v61, v29, v209
	v_pk_fma_f16 v222, v60, v28, v222
	v_pk_fma_f16 v223, v59, v27, v223
	v_pk_fma_f16 v224, v58, v26, v224
	v_pk_fma_f16 v225, v61, v37, v225
	v_pk_fma_f16 v227, v59, v35, v227
	v_pk_fma_f16 v228, v58, v34, v228
	v_pk_fma_f16 v229, v61, v213, v229
	v_pk_fma_f16 v232, v58, v210, v232
	v_pk_fma_f16 v233, v61, v217, v233
	v_pk_fma_f16 v236, v58, v214, v236
	s_waitcnt lgkmcnt(5)
	v_pk_fma_f16 v50, v54, v218, v50
	v_pk_fma_f16 v51, v55, v219, v51
	v_pk_fma_f16 v52, v56, v220, v52
	v_pk_fma_f16 v53, v57, v221, v53
	v_pk_fma_f16 v226, v60, v36, v226
	v_pk_fma_f16 v230, v60, v212, v230
	v_pk_fma_f16 v231, v59, v211, v231
	v_pk_fma_f16 v234, v60, v216, v234
	v_pk_fma_f16 v235, v59, v215, v235
	v_pk_fma_f16 v54, v61, v221, v77
	v_pk_fma_f16 v55, v60, v220, v76
	v_pk_fma_f16 v56, v59, v219, v75
	v_pk_fma_f16 v57, v58, v218, v74
	v_pk_fma_f16 v74, v62, v22, v240
	v_pk_fma_f16 v75, v63, v23, v239
	v_pk_fma_f16 v76, v64, v24, v238
	v_pk_fma_f16 v77, v65, v25, v237
	v_pk_fma_f16 v237, v62, v26, v244
	v_pk_fma_f16 v238, v63, v27, v243
	v_pk_fma_f16 v239, v64, v28, v242
	v_pk_fma_f16 v240, v65, v29, v241
	v_pk_fma_f16 v224, v62, v34, v224
	v_pk_fma_f16 v223, v63, v35, v223
	v_pk_fma_f16 v222, v64, v36, v222
	v_pk_fma_f16 v209, v65, v37, v209
	v_pk_fma_f16 v228, v62, v210, v228
	v_pk_fma_f16 v227, v63, v211, v227
	v_pk_fma_f16 v225, v65, v213, v225
	v_pk_fma_f16 v232, v62, v214, v232
	v_pk_fma_f16 v229, v65, v217, v229
	v_pk_fma_f16 v236, v62, v218, v236
	v_pk_fma_f16 v233, v65, v221, v233
	s_waitcnt lgkmcnt(4)
	v_pk_fma_f16 v53, v61, v97, v53
	v_pk_fma_f16 v52, v60, v96, v52
	v_pk_fma_f16 v51, v59, v95, v51
	v_pk_fma_f16 v50, v58, v94, v50
	v_pk_fma_f16 v226, v64, v212, v226
	v_pk_fma_f16 v231, v63, v215, v231
	v_pk_fma_f16 v230, v64, v216, v230
	v_pk_fma_f16 v235, v63, v219, v235
	v_pk_fma_f16 v234, v64, v220, v234
	v_pk_fma_f16 v57, v62, v94, v57
	v_pk_fma_f16 v56, v63, v95, v56
	v_pk_fma_f16 v55, v64, v96, v55
	v_pk_fma_f16 v54, v65, v97, v54
	v_pk_fma_f16 v58, v69, v29, v77
	v_pk_fma_f16 v59, v68, v28, v76
	v_pk_fma_f16 v60, v67, v27, v75
	v_pk_fma_f16 v61, v66, v26, v74
	v_pk_fma_f16 v74, v69, v37, v240
	v_pk_fma_f16 v75, v68, v36, v239
	v_pk_fma_f16 v76, v67, v35, v238
	v_pk_fma_f16 v77, v66, v34, v237
	v_pk_fma_f16 v209, v69, v213, v209
	v_pk_fma_f16 v222, v68, v212, v222
	v_pk_fma_f16 v223, v67, v211, v223
	v_pk_fma_f16 v224, v66, v210, v224
	v_pk_fma_f16 v225, v69, v217, v225
	v_pk_fma_f16 v227, v67, v215, v227
	v_pk_fma_f16 v228, v66, v214, v228
	v_pk_fma_f16 v229, v69, v221, v229
	v_pk_fma_f16 v232, v66, v218, v232
	v_pk_fma_f16 v233, v69, v97, v233
	v_pk_fma_f16 v236, v66, v94, v236
	s_waitcnt lgkmcnt(3)
	v_pk_fma_f16 v50, v62, v90, v50
	v_pk_fma_f16 v51, v63, v91, v51
	v_pk_fma_f16 v52, v64, v92, v52
	v_pk_fma_f16 v53, v65, v93, v53
	v_mov_b64_e32 v[30:31], v[94:95]
	v_mov_b64_e32 v[42:43], v[214:215]
	v_pk_fma_f16 v226, v68, v216, v226
	v_pk_fma_f16 v230, v68, v220, v230
	v_pk_fma_f16 v231, v67, v219, v231
	v_pk_fma_f16 v234, v68, v96, v234
	v_pk_fma_f16 v235, v67, v95, v235
	v_pk_fma_f16 v54, v69, v93, v54
	v_pk_fma_f16 v55, v68, v92, v55
	v_pk_fma_f16 v56, v67, v91, v56
	v_pk_fma_f16 v57, v66, v90, v57
	v_pk_fma_f16 v59, v72, v36, v59
	v_pk_fma_f16 v62, v70, v210, v77
	v_pk_fma_f16 v63, v71, v211, v76
	v_pk_fma_f16 v64, v72, v212, v75
	v_pk_fma_f16 v65, v73, v213, v74
	v_pk_fma_f16 v74, v70, v214, v224
	v_pk_fma_f16 v75, v71, v215, v223
	v_pk_fma_f16 v76, v72, v216, v222
	v_pk_fma_f16 v77, v73, v217, v209
	v_pk_fma_f16 v209, v70, v218, v228
	v_pk_fma_f16 v222, v71, v219, v227
	v_pk_fma_f16 v224, v73, v221, v225
	v_pk_fma_f16 v225, v70, v94, v232
	v_pk_fma_f16 v228, v73, v97, v229
	v_pk_fma_f16 v229, v70, v90, v236
	v_pk_fma_f16 v232, v73, v93, v233
	s_waitcnt lgkmcnt(2)
; #define LAS __attribute__((address_space(3)))
; __global__ void __launch_bounds__(NWAVES * 64, 2) fwd_kernel(Args args) {
;     ...
;                     f16x8 part[8];
; #pragma unroll
;                     for (int dj = 0; dj < 8; ++dj) {
;                         const f16x8 wj = *(const LAS f16x8*)(wb + (jj + dj) * CONV_CH);
; #pragma unroll
;                         for (int i = 0; i < 8; ++i) part[i] = (dj == 0) ? wj * win[i] : __builtin_elementwise_fma(wj, win[dj + i], part[i]);
;                     }
; #pragma unroll
;                     for (int i = 0; i < 8; ++i)
; #pragma unroll
;                         for (int e = 0; e < 8; ++e) acc[i][e] += (float)part[i][e];
;                 }
	v_pk_fma_f16 v53, v69, v89, v53
	v_pk_fma_f16 v52, v68, v88, v52
	v_pk_fma_f16 v51, v67, v87, v51
	v_pk_fma_f16 v50, v66, v86, v50
	v_mov_b64_e32 v[32:33], v[96:97]
	v_mov_b64_e32 v[38:39], v[218:219]
	v_mov_b64_e32 v[44:45], v[216:217]
	v_mov_b64_e32 v[18:19], v[90:91]
	v_pk_fma_f16 v61, v70, v34, v61
	v_pk_fma_f16 v60, v71, v35, v60
	v_pk_fma_f16 v58, v73, v37, v58
	v_pk_fma_f16 v223, v72, v220, v226
	v_pk_fma_f16 v226, v71, v95, v231
	v_pk_fma_f16 v227, v72, v96, v230
	v_pk_fma_f16 v230, v71, v91, v235
	v_pk_fma_f16 v231, v72, v92, v234
	v_pk_fma_f16 v57, v70, v86, v57
	v_pk_fma_f16 v56, v71, v87, v56
	v_pk_fma_f16 v55, v72, v88, v55
	v_pk_fma_f16 v54, v73, v89, v54
	v_pk_fma_f16 v59, v48, v212, v59
	v_pk_fma_f16 v65, v49, v217, v65
	v_pk_fma_f16 v64, v48, v216, v64
	v_pk_fma_f16 v63, v47, v215, v63
	v_pk_fma_f16 v62, v46, v214, v62
	v_pk_fma_f16 v77, v49, v221, v77
	v_pk_fma_f16 v76, v48, v220, v76
	v_pk_fma_f16 v69, v47, v219, v75
	v_pk_fma_f16 v95, v47, v95, v222
	v_pk_fma_f16 v75, v46, v94, v209
	v_pk_fma_f16 v209, v49, v89, v232
	v_pk_fma_f16 v212, v46, v86, v229
	s_waitcnt lgkmcnt(1)
	v_pk_fma_f16 v214, v70, v82, v50
	v_pk_fma_f16 v215, v71, v83, v51
	v_pk_fma_f16 v216, v72, v84, v52
	v_pk_fma_f16 v217, v73, v85, v53
	v_mov_b64_e32 v[40:41], v[220:221]
	v_mov_b64_e32 v[20:21], v[92:93]
	v_mov_b64_e32 v[22:23], v[86:87]
	v_mov_b64_e32 v[26:27], v[82:83]
	s_waitcnt lgkmcnt(0)
	v_mov_b64_e32 v[34:35], v[78:79]
	v_pk_fma_f16 v58, v49, v213, v58
	v_pk_fma_f16 v60, v47, v211, v60
	v_pk_fma_f16 v61, v46, v210, v61
	v_pk_fma_f16 v67, v46, v218, v74
	v_pk_fma_f16 v97, v49, v97, v224
	v_pk_fma_f16 v96, v48, v96, v223
	v_pk_fma_f16 v93, v49, v93, v228
	v_pk_fma_f16 v92, v48, v92, v227
	v_pk_fma_f16 v91, v47, v91, v226
	v_pk_fma_f16 v90, v46, v90, v225
	v_pk_fma_f16 v211, v48, v88, v231
	v_pk_fma_f16 v210, v47, v87, v230
	v_pk_fma_f16 v218, v49, v85, v54
	v_pk_fma_f16 v219, v48, v84, v55
	v_pk_fma_f16 v220, v47, v83, v56
	v_pk_fma_f16 v221, v46, v82, v57
	v_fma_mix_f32 v162, v76, 1.0, v162 op_sel_hi:[1,0,0]
	v_fma_mix_f32 v163, v76, 1.0, v163 op_sel:[1,0,0] op_sel_hi:[1,0,0]
	v_fma_mix_f32 v164, v77, 1.0, v164 op_sel_hi:[1,0,0]
	v_fma_mix_f32 v165, v77, 1.0, v165 op_sel:[1,0,0] op_sel_hi:[1,0,0]
	v_fma_mix_f32 v154, v95, 1.0, v154 op_sel_hi:[1,0,0]
	v_fma_mix_f32 v155, v95, 1.0, v155 op_sel:[1,0,0] op_sel_hi:[1,0,0]
	v_fma_mix_f32 v140, v212, 1.0, v140 op_sel_hi:[1,0,0]
	v_fma_mix_f32 v141, v212, 1.0, v141 op_sel:[1,0,0] op_sel_hi:[1,0,0]
	v_fma_mix_f32 v134, v209, 1.0, v134 op_sel_hi:[1,0,0]
	v_fma_mix_f32 v135, v209, 1.0, v135 op_sel:[1,0,0] op_sel_hi:[1,0,0]
	v_pk_fma_f16 v209, v49, v81, v217
	v_pk_fma_f16 v222, v48, v80, v216
	v_pk_fma_f16 v217, v47, v79, v215
	v_pk_fma_f16 v215, v46, v78, v214
	v_mov_b64_e32 v[24:25], v[88:89]
	v_mov_b64_e32 v[28:29], v[84:85]
	v_mov_b64_e32 v[36:37], v[80:81]
	v_fma_mix_f32 v180, v61, 1.0, v180 op_sel_hi:[1,0,0]
	v_fma_mix_f32 v181, v61, 1.0, v181 op_sel:[1,0,0] op_sel_hi:[1,0,0]
	v_fma_mix_f32 v178, v60, 1.0, v178 op_sel_hi:[1,0,0]
	v_fma_mix_f32 v179, v60, 1.0, v179 op_sel:[1,0,0] op_sel_hi:[1,0,0]
	v_fma_mix_f32 v176, v59, 1.0, v176 op_sel_hi:[1,0,0]
	v_fma_mix_f32 v177, v59, 1.0, v177 op_sel:[1,0,0] op_sel_hi:[1,0,0]
	v_fma_mix_f32 v174, v58, 1.0, v174 op_sel_hi:[1,0,0]
	v_fma_mix_f32 v175, v58, 1.0, v175 op_sel:[1,0,0] op_sel_hi:[1,0,0]
	v_fma_mix_f32 v172, v62, 1.0, v172 op_sel_hi:[1,0,0]
	v_fma_mix_f32 v173, v62, 1.0, v173 op_sel:[1,0,0] op_sel_hi:[1,0,0]
	v_fma_mix_f32 v170, v63, 1.0, v170 op_sel_hi:[1,0,0]
	v_fma_mix_f32 v171, v63, 1.0, v171 op_sel:[1,0,0] op_sel_hi:[1,0,0]
	v_fma_mix_f32 v168, v64, 1.0, v168 op_sel_hi:[1,0,0]
	v_fma_mix_f32 v169, v64, 1.0, v169 op_sel:[1,0,0] op_sel_hi:[1,0,0]
	v_fma_mix_f32 v166, v65, 1.0, v166 op_sel_hi:[1,0,0]
	v_fma_mix_f32 v167, v65, 1.0, v167 op_sel:[1,0,0] op_sel_hi:[1,0,0]
	v_fma_mix_f32 v158, v67, 1.0, v158 op_sel_hi:[1,0,0]
	v_fma_mix_f32 v159, v67, 1.0, v159 op_sel:[1,0,0] op_sel_hi:[1,0,0]
	v_fma_mix_f32 v160, v69, 1.0, v160 op_sel_hi:[1,0,0]
	v_fma_mix_f32 v161, v69, 1.0, v161 op_sel:[1,0,0] op_sel_hi:[1,0,0]
	v_fma_mix_f32 v156, v75, 1.0, v156 op_sel_hi:[1,0,0]
	v_fma_mix_f32 v157, v75, 1.0, v157 op_sel:[1,0,0] op_sel_hi:[1,0,0]
	v_fma_mix_f32 v152, v96, 1.0, v152 op_sel_hi:[1,0,0]
	v_fma_mix_f32 v153, v96, 1.0, v153 op_sel:[1,0,0] op_sel_hi:[1,0,0]
	v_fma_mix_f32 v150, v97, 1.0, v150 op_sel_hi:[1,0,0]
	v_fma_mix_f32 v151, v97, 1.0, v151 op_sel:[1,0,0] op_sel_hi:[1,0,0]
	v_fma_mix_f32 v148, v90, 1.0, v148 op_sel_hi:[1,0,0]
	v_fma_mix_f32 v149, v90, 1.0, v149 op_sel:[1,0,0] op_sel_hi:[1,0,0]
	v_fma_mix_f32 v146, v91, 1.0, v146 op_sel_hi:[1,0,0]
	v_fma_mix_f32 v147, v91, 1.0, v147 op_sel:[1,0,0] op_sel_hi:[1,0,0]
	v_fma_mix_f32 v144, v92, 1.0, v144 op_sel_hi:[1,0,0]
	v_fma_mix_f32 v145, v92, 1.0, v145 op_sel:[1,0,0] op_sel_hi:[1,0,0]
	v_fma_mix_f32 v142, v93, 1.0, v142 op_sel_hi:[1,0,0]
	v_fma_mix_f32 v143, v93, 1.0, v143 op_sel:[1,0,0] op_sel_hi:[1,0,0]
	v_fma_mix_f32 v138, v210, 1.0, v138 op_sel_hi:[1,0,0]
	v_fma_mix_f32 v139, v210, 1.0, v139 op_sel:[1,0,0] op_sel_hi:[1,0,0]
	v_fma_mix_f32 v136, v211, 1.0, v136 op_sel_hi:[1,0,0]
	v_fma_mix_f32 v137, v211, 1.0, v137 op_sel:[1,0,0] op_sel_hi:[1,0,0]
	v_fma_mix_f32 v132, v221, 1.0, v132 op_sel_hi:[1,0,0]
	v_fma_mix_f32 v133, v221, 1.0, v133 op_sel:[1,0,0] op_sel_hi:[1,0,0]
	v_fma_mix_f32 v130, v220, 1.0, v130 op_sel_hi:[1,0,0]
	v_fma_mix_f32 v131, v220, 1.0, v131 op_sel:[1,0,0] op_sel_hi:[1,0,0]
	v_fma_mix_f32 v128, v219, 1.0, v128 op_sel_hi:[1,0,0]
	v_fma_mix_f32 v129, v219, 1.0, v129 op_sel:[1,0,0] op_sel_hi:[1,0,0]
	v_fma_mix_f32 v126, v218, 1.0, v126 op_sel_hi:[1,0,0]
	v_fma_mix_f32 v127, v218, 1.0, v127 op_sel:[1,0,0] op_sel_hi:[1,0,0]
	v_fma_mix_f32 v124, v215, 1.0, v124 op_sel_hi:[1,0,0]
	v_fma_mix_f32 v125, v215, 1.0, v125 op_sel:[1,0,0] op_sel_hi:[1,0,0]
	v_fma_mix_f32 v122, v217, 1.0, v122 op_sel_hi:[1,0,0]
	v_fma_mix_f32 v123, v217, 1.0, v123 op_sel:[1,0,0] op_sel_hi:[1,0,0]
	v_fma_mix_f32 v120, v222, 1.0, v120 op_sel_hi:[1,0,0]
	v_fma_mix_f32 v121, v222, 1.0, v121 op_sel:[1,0,0] op_sel_hi:[1,0,0]
	v_fma_mix_f32 v118, v209, 1.0, v118 op_sel_hi:[1,0,0]
	v_fma_mix_f32 v119, v209, 1.0, v119 op_sel:[1,0,0] op_sel_hi:[1,0,0]
	s_add_i32 s0, s0, 8
	v_add_u32_e32 v208, 0x2000, v208
	s_cmp_lt_u32 s0, 24
	s_cbranch_scc1 .LBB0_648
; __global__ void __launch_bounds__(NWAVES * 64, 2) fwd_kernel(Args args) {
;     ...
;                 float gam[8], bet[8], cb[8];
; #pragma unroll
;                 for (int e = 0; e < 8; ++e) { gam[e] = conv_ln_g[c0 + e]; bet[e] = conv_ln_b[c0 + e]; cb[e] = conv_b[c0 + e]; }
;                 float sm[8], sq[8];
; #pragma unroll
;                 for (int i = 0; i < 8; ++i) { float s_ = 0.f;
; #pragma unroll
;                     for (int e = 0; e < 8; ++e) { acc[i][e] += cb[e]; s_ += acc[i][e]; }
;                     sm[i] = s_; }
;                 wave_sum_n<8>(sm);
; #pragma unroll
;                 for (int i = 0; i < 8; ++i) { const float mu = sm[i] * (1.0f / CONV_CH); sm[i] = mu; float q_ = 0.f;
; #pragma unroll
;                     for (int e = 0; e < 8; ++e) { acc[i][e] -= mu; q_ += acc[i][e] * acc[i][e]; }
;                     sq[i] = q_; }
;                 wave_sum_n<8>(sq);
; #pragma unroll
;     ...
;         { const size_t n8 = (size_t)M * PLE / 8, stride = (size_t)nwk;
;           for (size_t i = (size_t)wk; i < n8; i += 4 * stride) {
;             f32x4 a[4], b[4];
; #pragma unroll
;             for (int q = 0; q < 4; ++q) { const size_t ii = (i + q * stride < n8) ? i + q * stride : n8 - 1; a[q] = __builtin_nontemporal_load((const f32x4*)p + 2 * ii); b[q] = __builtin_nontemporal_load((const f32x4*)p + 2 * ii + 1); }
	s_waitcnt vmcnt(0)
	v_mov_b64_e32 v[22:23], v[2:3]
	v_mov_b64_e32 v[24:25], v[4:5]
	v_mov_b64_e32 v[18:19], v[6:7]
	v_mov_b64_e32 v[20:21], v[8:9]
	v_lshl_add_u32 v209, s85, 9, v0
	v_lshlrev_b32_e32 v209, 5, v209
	global_load_dwordx4 v[210:213], v209, s[38:39] nt
	global_load_dwordx4 v[214:217], v209, s[38:39] offset:16 nt
	s_add_u32 s98, s38, 0x400000
	s_addc_u32 s99, s39, 0
	global_load_dwordx4 v[218:221], v209, s[98:99] nt
	global_load_dwordx4 v[222:225], v209, s[98:99] offset:16 nt
	s_add_u32 s98, s38, 0x800000
	s_addc_u32 s99, s39, 0
	global_load_dwordx4 v[226:229], v209, s[98:99] nt
	global_load_dwordx4 v[230:233], v209, s[98:99] offset:16 nt
	s_add_u32 s98, s38, 0xc00000
	s_addc_u32 s99, s39, 0
	global_load_dwordx4 v[234:237], v209, s[98:99] nt
	global_load_dwordx4 v[238:241], v209, s[98:99] offset:16 nt
	s_add_i32 s0, s14, s6
	s_ashr_i32 s1, s0, 31
	s_lshl_b64 s[8:9], s[0:1], 11
	s_add_i32 s11, s11, s69
	s_waitcnt vmcnt(1)
	v_pk_add_f32 v[44:45], v[22:23], v[176:177]
	s_waitcnt vmcnt(0)
	v_pk_add_f32 v[48:49], v[18:19], v[180:181]
	v_pk_add_f32 v[56:57], v[18:19], v[172:173]
	v_add_f32_e32 v26, 0, v48
	v_add_f32_e32 v27, 0, v56
	v_pk_add_f32 v[46:47], v[20:21], v[178:179]
	v_pk_add_f32 v[54:55], v[20:21], v[170:171]
	v_add_f32_e32 v26, v26, v49
	v_add_f32_e32 v27, v27, v57
	v_add_f32_e32 v26, v26, v46
	v_add_f32_e32 v27, v27, v54
	v_pk_add_f32 v[52:53], v[22:23], v[168:169]
	v_add_f32_e32 v26, v26, v47
	v_add_f32_e32 v27, v27, v55
	v_add_f32_e32 v26, v26, v44
	v_add_f32_e32 v27, v27, v52
	v_pk_add_f32 v[42:43], v[24:25], v[174:175]
	v_pk_add_f32 v[50:51], v[24:25], v[166:167]
	v_add_f32_e32 v26, v26, v45
	v_add_f32_e32 v27, v27, v53
	v_add_f32_e32 v26, v26, v42
	v_add_f32_e32 v27, v27, v50
	v_add_f32_e32 v26, v26, v43
	v_add_f32_e32 v27, v27, v51
	ds_bpermute_b32 v28, v184, v26
	ds_bpermute_b32 v29, v184, v27
	s_waitcnt lgkmcnt(1)
	v_add_f32_e32 v26, v26, v28
	s_waitcnt lgkmcnt(0)
	v_add_f32_e32 v27, v27, v29
	ds_bpermute_b32 v28, v185, v26
	ds_bpermute_b32 v29, v185, v27
	s_waitcnt lgkmcnt(1)
	v_add_f32_e32 v26, v26, v28
	s_waitcnt lgkmcnt(0)
	v_add_f32_e32 v27, v27, v29
	ds_bpermute_b32 v28, v186, v26
	ds_bpermute_b32 v29, v186, v27
	s_waitcnt lgkmcnt(1)
	v_add_f32_e32 v26, v26, v28
	s_waitcnt lgkmcnt(0)
	v_add_f32_e32 v27, v27, v29
	ds_bpermute_b32 v28, v187, v26
	ds_bpermute_b32 v29, v187, v27
	s_waitcnt lgkmcnt(1)
	v_add_f32_e32 v58, v26, v28
	s_waitcnt lgkmcnt(0)
	v_add_f32_e32 v59, v27, v29
	v_mov_b64_e32 v[26:27], v[10:11]
	v_mov_b64_e32 v[28:29], v[12:13]
	v_mov_b64_e32 v[34:35], v[14:15]
	v_mov_b64_e32 v[36:37], v[16:17]
	v_mov_b64_e32 v[30:31], v[250:251]
	v_mov_b64_e32 v[32:33], v[252:253]
	v_mov_b64_e32 v[38:39], v[108:109]
	v_mov_b64_e32 v[40:41], v[110:111]
	ds_bpermute_b32 v60, v188, v58
	ds_bpermute_b32 v61, v188, v59
	s_waitcnt lgkmcnt(1)
	v_add_f32_e32 v60, v58, v60
	s_waitcnt lgkmcnt(0)
	v_add_f32_e32 v61, v59, v61
	ds_bpermute_b32 v62, v189, v60
	ds_bpermute_b32 v63, v189, v61
	v_lshl_add_u64 v[58:59], v[104:105], 0, s[8:9]
	s_or_b32 s8, s0, 1
	s_ashr_i32 s9, s8, 31
	s_waitcnt lgkmcnt(1)
	v_add_f32_e32 v60, v60, v62
	s_waitcnt lgkmcnt(0)
	v_add_f32_e32 v61, v61, v63
	v_mul_f32_e32 v60, 0x3b000000, v60
	v_mul_f32_e32 v62, 0x3b000000, v61
	v_pk_add_f32 v[48:49], v[48:49], v[60:61] op_sel_hi:[1,0] neg_lo:[0,1] neg_hi:[0,1]
	v_pk_add_f32 v[46:47], v[46:47], v[60:61] op_sel_hi:[1,0] neg_lo:[0,1] neg_hi:[0,1]
	v_pk_add_f32 v[44:45], v[44:45], v[60:61] op_sel_hi:[1,0] neg_lo:[0,1] neg_hi:[0,1]
	v_pk_add_f32 v[60:61], v[42:43], v[60:61] op_sel_hi:[1,0] neg_lo:[0,1] neg_hi:[0,1]
	v_pk_add_f32 v[42:43], v[50:51], v[62:63] op_sel_hi:[1,0] neg_lo:[0,1] neg_hi:[0,1]
	v_pk_mul_f32 v[50:51], v[48:49], v[48:49]
	v_pk_add_f32 v[56:57], v[56:57], v[62:63] op_sel_hi:[1,0] neg_lo:[0,1] neg_hi:[0,1]
	v_pk_add_f32 v[54:55], v[54:55], v[62:63] op_sel_hi:[1,0] neg_lo:[0,1] neg_hi:[0,1]
	v_pk_add_f32 v[52:53], v[52:53], v[62:63] op_sel_hi:[1,0] neg_lo:[0,1] neg_hi:[0,1]
	v_pk_mul_f32 v[62:63], v[46:47], v[46:47]
	v_add_f32_e32 v50, v50, v51
	v_pk_mul_f32 v[68:69], v[56:57], v[56:57]
	v_add_f32_e32 v50, v50, v62
	v_pk_mul_f32 v[64:65], v[44:45], v[44:45]
	v_pk_mul_f32 v[70:71], v[54:55], v[54:55]
	v_add_f32_e32 v51, v68, v69
	v_add_f32_e32 v50, v50, v63
	v_add_f32_e32 v51, v51, v70
	v_add_f32_e32 v50, v50, v64
	v_pk_mul_f32 v[66:67], v[60:61], v[60:61]
	v_pk_mul_f32 v[72:73], v[52:53], v[52:53]
	v_add_f32_e32 v51, v51, v71
	v_add_f32_e32 v50, v50, v65
	v_add_f32_e32 v51, v51, v72
	v_add_f32_e32 v50, v50, v66
	v_pk_mul_f32 v[74:75], v[42:43], v[42:43]
	v_add_f32_e32 v51, v51, v73
	v_add_f32_e32 v62, v50, v67
	ds_bpermute_b32 v63, v184, v62
	v_add_f32_e32 v50, v51, v74
	v_add_f32_e32 v64, v50, v75
	ds_bpermute_b32 v65, v184, v64
	v_pk_add_f32 v[50:51], v[24:25], v[164:165]
	s_waitcnt lgkmcnt(1)
	v_add_f32_e32 v66, v62, v63
	ds_bpermute_b32 v67, v185, v66
	v_pk_add_f32 v[62:63], v[22:23], v[162:163]
	s_waitcnt lgkmcnt(1)
	v_add_f32_e32 v68, v64, v65
	ds_bpermute_b32 v69, v185, v68
	v_pk_add_f32 v[64:65], v[20:21], v[160:161]
	s_waitcnt lgkmcnt(1)
	v_add_f32_e32 v70, v66, v67
	ds_bpermute_b32 v71, v186, v70
	v_pk_add_f32 v[66:67], v[18:19], v[158:159]
	s_waitcnt lgkmcnt(1)
	v_add_f32_e32 v68, v68, v69
	ds_bpermute_b32 v69, v186, v68
	v_add_f32_e32 v72, 0, v66
	s_waitcnt lgkmcnt(1)
	v_add_f32_e32 v70, v70, v71
	ds_bpermute_b32 v71, v187, v70
	v_add_f32_e32 v72, v72, v67
	s_waitcnt lgkmcnt(1)
	v_add_f32_e32 v68, v68, v69
	ds_bpermute_b32 v69, v187, v68
	v_add_f32_e32 v72, v72, v64
	s_waitcnt lgkmcnt(1)
	v_add_f32_e32 v70, v70, v71
	ds_bpermute_b32 v71, v188, v70
	v_add_f32_e32 v72, v72, v65
	s_waitcnt lgkmcnt(1)
; __device__ __forceinline__ unsigned pkh8(float lo, float hi) { return rnd8a(pkh(lo, hi)); }
; __device__ __forceinline__ float sigmoidf_(float x) { return __builtin_amdgcn_rcpf(1.0f + __builtin_amdgcn_exp2f(-x * LOG2E)); }
; __global__ void __launch_bounds__(NWAVES * 64, 2) fwd_kernel(Args args) {
;     ...
;                 wave_sum_n<8>(sm);
; #pragma unroll
;                 for (int i = 0; i < 8; ++i) { const float mu = sm[i] * (1.0f / CONV_CH); sm[i] = mu; float q_ = 0.f;
; #pragma unroll
;                     for (int e = 0; e < 8; ++e) { acc[i][e] -= mu; q_ += acc[i][e] * acc[i][e]; }
;                     sq[i] = q_; }
;                 wave_sum_n<8>(sq);
; #pragma unroll
;                 for (int i = 0; i < 8; ++i) {
;                     const float rstd = __builtin_amdgcn_rsqf(sq[i] * (1.0f / CONV_CH) + EPS);
;                     float y[8];
; #pragma unroll
;                     for (int e = 0; e < 8; ++e) { const float z = acc[i][e] * rstd * gam[e] + bet[e]; y[e] = z * sigmoidf_(z); }
;                     u32x4 w; w.x = pkh8(y[0], y[1]); w.y = pkh8(y[2], y[3]); w.z = pkh8(y[4], y[5]); w.w = pkh8(y[6], y[7]);
	v_add_f32_e32 v68, v68, v69
	ds_bpermute_b32 v69, v188, v68
	v_add_f32_e32 v72, v72, v62
	s_waitcnt lgkmcnt(1)
	v_add_f32_e32 v70, v70, v71
	ds_bpermute_b32 v71, v189, v70
	v_add_f32_e32 v72, v72, v63
	s_waitcnt lgkmcnt(1)
	v_add_f32_e32 v69, v68, v69
	ds_bpermute_b32 v73, v189, v69
	v_add_f32_e32 v78, v72, v50
	s_waitcnt lgkmcnt(1)
	v_add_f32_e32 v68, v70, v71
	v_fmamk_f32 v68, v68, 0x3b000000, v207
	v_rsq_f32_e32 v68, v68
	s_waitcnt lgkmcnt(0)
	v_add_f32_e32 v69, v69, v73
	v_fmamk_f32 v69, v69, 0x3b000000, v207
	v_rsq_f32_e32 v70, v69
	v_pk_mul_f32 v[48:49], v[68:69], v[48:49] op_sel_hi:[0,1]
	v_pk_mul_f32 v[46:47], v[68:69], v[46:47] op_sel_hi:[0,1]
	v_pk_mul_f32 v[44:45], v[68:69], v[44:45] op_sel_hi:[0,1]
	v_pk_mul_f32 v[60:61], v[68:69], v[60:61] op_sel_hi:[0,1]
	v_pk_fma_f32 v[48:49], v[48:49], v[34:35], v[38:39]
	v_pk_fma_f32 v[46:47], v[46:47], v[36:37], v[40:41]
	v_pk_fma_f32 v[44:45], v[44:45], v[26:27], v[30:31]
	v_pk_mul_f32 v[56:57], v[70:71], v[56:57] op_sel_hi:[0,1]
	v_pk_fma_f32 v[60:61], v[60:61], v[28:29], v[32:33]
	v_mul_f32_e32 v68, 0xbfb8aa3b, v48
	v_mul_f32_e32 v69, 0xbfb8aa3b, v49
	v_mul_f32_e32 v71, 0xbfb8aa3b, v46
	v_mul_f32_e32 v72, 0xbfb8aa3b, v47
	v_mul_f32_e32 v73, 0xbfb8aa3b, v44
	v_mul_f32_e32 v74, 0xbfb8aa3b, v45
	v_pk_fma_f32 v[56:57], v[56:57], v[34:35], v[38:39]
	v_mul_f32_e32 v75, 0xbfb8aa3b, v60
	v_mul_f32_e32 v76, 0xbfb8aa3b, v61
	v_exp_f32_e32 v68, v68
	v_exp_f32_e32 v69, v69
	v_exp_f32_e32 v71, v71
	v_exp_f32_e32 v72, v72
	v_exp_f32_e32 v73, v73
	v_exp_f32_e32 v74, v74
	v_mul_f32_e32 v77, 0xbfb8aa3b, v56
	v_exp_f32_e32 v75, v75
	v_exp_f32_e32 v76, v76
	v_exp_f32_e32 v77, v77
	v_add_f32_e32 v68, 1.0, v68
	v_add_f32_e32 v69, 1.0, v69
	v_add_f32_e32 v71, 1.0, v71
	v_add_f32_e32 v80, 1.0, v72
	v_add_f32_e32 v81, 1.0, v73
	v_add_f32_e32 v82, 1.0, v74
	v_add_f32_e32 v83, 1.0, v75
	v_add_f32_e32 v84, 1.0, v76
	v_rcp_f32_e32 v68, v68
	v_rcp_f32_e32 v69, v69
	v_rcp_f32_e32 v72, v71
	v_rcp_f32_e32 v73, v80
	v_rcp_f32_e32 v74, v81
	v_rcp_f32_e32 v75, v82
	v_add_f32_e32 v85, 1.0, v77
	v_rcp_f32_e32 v76, v83
	v_rcp_f32_e32 v77, v84
	v_pk_mul_f32 v[48:49], v[48:49], v[68:69]
	v_pk_mul_f32 v[46:47], v[46:47], v[72:73]
	v_pk_mul_f32 v[44:45], v[44:45], v[74:75]
	v_pk_mul_f32 v[60:61], v[60:61], v[76:77]
	v_cvt_pk_f16_f32 v48, v48, v49
	v_cvt_pk_f16_f32 v46, v46, v47
	v_cvt_pk_f16_f32 v44, v44, v45
	v_cvt_pk_f16_f32 v45, v60, v61
	v_add_u32_e32 v47, 0x40004, v48
	v_add_u32_e32 v46, 0x40004, v46
	v_add_u32_e32 v48, 0x40004, v44
	v_add_u32_e32 v49, 0x40004, v45
	v_and_b32_e32 v45, 0xfff8fff8, v46
	v_and_b32_e32 v46, 0xfff8fff8, v48
	v_add_f32_e32 v48, v78, v51
	v_and_b32_e32 v44, 0xfff8fff8, v47
	v_and_b32_e32 v47, 0xfff8fff8, v49
	ds_bpermute_b32 v49, v184, v48
	v_mul_f32_e32 v79, 0xbfb8aa3b, v57
	v_exp_f32_e32 v79, v79
	global_store_dwordx4 v[58:59], v[44:47], off
	v_pk_mul_f32 v[52:53], v[70:71], v[52:53] op_sel_hi:[0,1]
	s_waitcnt lgkmcnt(0)
	v_add_f32_e32 v48, v48, v49
	ds_bpermute_b32 v49, v185, v48
	v_pk_mul_f32 v[46:47], v[70:71], v[54:55] op_sel_hi:[0,1]
	v_pk_fma_f32 v[46:47], v[46:47], v[36:37], v[40:41]
	v_add_f32_e32 v45, 1.0, v79
	v_mul_f32_e32 v54, 0xbfb8aa3b, v46
	s_waitcnt lgkmcnt(0)
	v_add_f32_e32 v49, v48, v49
	ds_bpermute_b32 v55, v186, v49
	v_rcp_f32_e32 v44, v85
	v_rcp_f32_e32 v45, v45
	v_exp_f32_e32 v54, v54
	v_pk_fma_f32 v[52:53], v[52:53], v[26:27], v[30:31]
	s_waitcnt lgkmcnt(0)
	v_add_f32_e32 v55, v49, v55
	v_pk_mul_f32 v[44:45], v[56:57], v[44:45]
	v_add_f32_e32 v48, 1.0, v54
	v_mul_f32_e32 v54, 0xbfb8aa3b, v47
	ds_bpermute_b32 v56, v187, v55
	v_exp_f32_e32 v54, v54
	v_mul_f32_e32 v57, 0xbfb8aa3b, v53
	v_rcp_f32_e32 v48, v48
	v_exp_f32_e32 v57, v57
	v_add_f32_e32 v49, 1.0, v54
	s_waitcnt lgkmcnt(0)
	v_add_f32_e32 v54, v55, v56
	ds_bpermute_b32 v55, v188, v54
	v_mul_f32_e32 v56, 0xbfb8aa3b, v52
	v_rcp_f32_e32 v49, v49
	v_exp_f32_e32 v56, v56
	v_pk_mul_f32 v[42:43], v[70:71], v[42:43] op_sel_hi:[0,1]
	s_waitcnt lgkmcnt(0)
	v_add_f32_e32 v54, v54, v55
	ds_bpermute_b32 v55, v189, v54
	v_pk_mul_f32 v[46:47], v[46:47], v[48:49]
	v_add_f32_e32 v48, 1.0, v56
	v_add_f32_e32 v49, 1.0, v57
	v_pk_fma_f32 v[42:43], v[42:43], v[28:29], v[32:33]
	s_waitcnt lgkmcnt(0)
	v_add_f32_e32 v54, v54, v55
	v_mul_f32_e32 v54, 0x3b000000, v54
	v_pk_add_f32 v[56:57], v[66:67], v[54:55] op_sel_hi:[1,0] neg_lo:[0,1] neg_hi:[0,1]
	v_pk_add_f32 v[60:61], v[64:65], v[54:55] op_sel_hi:[1,0] neg_lo:[0,1] neg_hi:[0,1]
	v_pk_mul_f32 v[58:59], v[56:57], v[56:57]
	v_pk_mul_f32 v[64:65], v[60:61], v[60:61]
	v_add_f32_e32 v58, v58, v59
	v_pk_add_f32 v[62:63], v[62:63], v[54:55] op_sel_hi:[1,0] neg_lo:[0,1] neg_hi:[0,1]
	v_add_f32_e32 v58, v58, v64
	v_pk_mul_f32 v[66:67], v[62:63], v[62:63]
	v_add_f32_e32 v58, v58, v65
	v_pk_add_f32 v[50:51], v[50:51], v[54:55] op_sel_hi:[1,0] neg_lo:[0,1] neg_hi:[0,1]
	v_add_f32_e32 v58, v58, v66
	v_pk_mul_f32 v[54:55], v[50:51], v[50:51]
	v_add_f32_e32 v58, v58, v67
	v_add_f32_e32 v54, v58, v54
	v_add_f32_e32 v54, v54, v55
	ds_bpermute_b32 v55, v184, v54
	v_mul_f32_e32 v58, 0xbfb8aa3b, v42
	v_exp_f32_e32 v58, v58
	v_mul_f32_e32 v59, 0xbfb8aa3b, v43
	v_exp_f32_e32 v59, v59
	s_waitcnt lgkmcnt(0)
	v_add_f32_e32 v54, v54, v55
	ds_bpermute_b32 v55, v185, v54
	v_add_f32_e32 v58, 1.0, v58
	v_rcp_f32_e32 v48, v48
	v_rcp_f32_e32 v49, v49
	s_lshl_b64 s[8:9], s[8:9], 11
	s_waitcnt lgkmcnt(0)
	v_add_f32_e32 v64, v54, v55
	ds_bpermute_b32 v65, v186, v64
	v_rcp_f32_e32 v54, v58
	v_add_f32_e32 v55, 1.0, v59
	v_rcp_f32_e32 v55, v55
	v_pk_mul_f32 v[48:49], v[52:53], v[48:49]
	s_waitcnt lgkmcnt(0)
	v_add_f32_e32 v58, v64, v65
	ds_bpermute_b32 v59, v187, v58
	v_pk_mul_f32 v[52:53], v[42:43], v[54:55]
	v_cvt_pk_f16_f32 v42, v44, v45
	v_cvt_pk_f16_f32 v43, v46, v47
	v_cvt_pk_f16_f32 v46, v48, v49
	s_waitcnt lgkmcnt(0)
; __device__ __forceinline__ unsigned pkh8(float lo, float hi) { return rnd8a(pkh(lo, hi)); }
; __device__ __forceinline__ float sigmoidf_(float x) { return __builtin_amdgcn_rcpf(1.0f + __builtin_amdgcn_exp2f(-x * LOG2E)); }
; __global__ void __launch_bounds__(NWAVES * 64, 2) fwd_kernel(Args args) {
;     ...
;                 for (int i = 0; i < 8; ++i) { float s_ = 0.f;
; #pragma unroll
;                     for (int e = 0; e < 8; ++e) { acc[i][e] += cb[e]; s_ += acc[i][e]; }
;                     sm[i] = s_; }
;                 wave_sum_n<8>(sm);
; #pragma unroll
;                 for (int i = 0; i < 8; ++i) { const float mu = sm[i] * (1.0f / CONV_CH); sm[i] = mu; float q_ = 0.f;
; #pragma unroll
;                     for (int e = 0; e < 8; ++e) { acc[i][e] -= mu; q_ += acc[i][e] * acc[i][e]; }
;                     sq[i] = q_; }
;                 wave_sum_n<8>(sq);
; #pragma unroll
;                 for (int i = 0; i < 8; ++i) {
;                     const float rstd = __builtin_amdgcn_rsqf(sq[i] * (1.0f / CONV_CH) + EPS);
;                     float y[8];
; #pragma unroll
;                     for (int e = 0; e < 8; ++e) { const float z = acc[i][e] * rstd * gam[e] + bet[e]; y[e] = z * sigmoidf_(z); }
;                     u32x4 w; w.x = pkh8(y[0], y[1]); w.y = pkh8(y[2], y[3]); w.z = pkh8(y[4], y[5]); w.w = pkh8(y[6], y[7]);
;                     *(u32x4*)(MIX + (size_t)(t0 + wave * 8 + i) * D + c0) = w;
	v_add_f32_e32 v44, v58, v59
	ds_bpermute_b32 v45, v188, v44
	v_add_u32_e32 v42, 0x40004, v42
	v_add_u32_e32 v43, 0x40004, v43
	v_pk_add_f32 v[54:55], v[18:19], v[156:157]
	v_and_b32_e32 v42, 0xfff8fff8, v42
	s_waitcnt lgkmcnt(0)
	v_add_f32_e32 v45, v44, v45
	ds_bpermute_b32 v47, v189, v45
	v_add_u32_e32 v44, 0x40004, v46
	v_cvt_pk_f16_f32 v46, v52, v53
	v_add_u32_e32 v48, 0x40004, v46
	v_and_b32_e32 v43, 0xfff8fff8, v43
	s_waitcnt lgkmcnt(0)
	v_add_f32_e32 v45, v45, v47
	v_fmamk_f32 v45, v45, 0x3b000000, v207
	v_rsq_f32_e32 v46, v45
	v_and_b32_e32 v44, 0xfff8fff8, v44
	v_and_b32_e32 v45, 0xfff8fff8, v48
	v_lshl_add_u64 v[52:53], v[104:105], 0, s[8:9]
	v_pk_mul_f32 v[48:49], v[46:47], v[56:57] op_sel_hi:[0,1]
	v_add_f32_e32 v56, 0, v54
	global_store_dwordx4 v[52:53], v[42:45], off
	v_pk_add_f32 v[52:53], v[20:21], v[154:155]
	v_add_f32_e32 v56, v56, v55
	v_add_f32_e32 v56, v56, v52
	v_pk_fma_f32 v[48:49], v[48:49], v[34:35], v[38:39]
	v_pk_add_f32 v[44:45], v[22:23], v[152:153]
	v_add_f32_e32 v56, v56, v53
	v_mul_f32_e32 v42, 0xbfb8aa3b, v49
	v_add_f32_e32 v56, v56, v44
	v_exp_f32_e32 v57, v42
	v_pk_add_f32 v[42:43], v[24:25], v[150:151]
	v_add_f32_e32 v56, v56, v45
	v_mul_f32_e32 v47, 0xbfb8aa3b, v48
	v_add_f32_e32 v56, v56, v42
	v_exp_f32_e32 v47, v47
	v_add_f32_e32 v64, v56, v43
	ds_bpermute_b32 v65, v184, v64
	s_or_b32 s8, s0, 2
	v_add_f32_e32 v47, 1.0, v47
	v_rcp_f32_e32 v56, v47
	v_add_f32_e32 v47, 1.0, v57
	v_rcp_f32_e32 v57, v47
	v_pk_mul_f32 v[58:59], v[46:47], v[60:61] op_sel_hi:[0,1]
	s_waitcnt lgkmcnt(0)
	v_add_f32_e32 v47, v64, v65
	ds_bpermute_b32 v60, v185, v47
	v_pk_mul_f32 v[48:49], v[48:49], v[56:57]
	v_pk_fma_f32 v[58:59], v[58:59], v[36:37], v[40:41]
	s_ashr_i32 s9, s8, 31
	v_mul_f32_e32 v61, 0xbfb8aa3b, v58
	s_waitcnt lgkmcnt(0)
	v_add_f32_e32 v47, v47, v60
	ds_bpermute_b32 v57, v186, v47
	v_mul_f32_e32 v60, 0xbfb8aa3b, v59
	v_exp_f32_e32 v61, v61
	v_exp_f32_e32 v60, v60
	s_lshl_b64 s[8:9], s[8:9], 11
	s_waitcnt lgkmcnt(0)
	v_add_f32_e32 v47, v47, v57
	ds_bpermute_b32 v64, v187, v47
	v_add_f32_e32 v56, 1.0, v61
	v_add_f32_e32 v57, 1.0, v60
	v_pk_mul_f32 v[60:61], v[46:47], v[62:63] op_sel_hi:[0,1]
	v_pk_fma_f32 v[60:61], v[60:61], v[26:27], v[30:31]
	s_waitcnt lgkmcnt(0)
	v_add_f32_e32 v47, v47, v64
	ds_bpermute_b32 v62, v188, v47
	v_mul_f32_e32 v63, 0xbfb8aa3b, v60
	v_exp_f32_e32 v63, v63
	v_mul_f32_e32 v64, 0xbfb8aa3b, v61
	v_rcp_f32_e32 v56, v56
	s_waitcnt lgkmcnt(0)
	v_add_f32_e32 v47, v47, v62
	ds_bpermute_b32 v62, v189, v47
	v_rcp_f32_e32 v57, v57
	v_exp_f32_e32 v64, v64
	s_waitcnt lgkmcnt(0)
	v_add_f32_e32 v47, v47, v62
	v_mul_f32_e32 v62, 0x3b000000, v47
	v_pk_add_f32 v[54:55], v[54:55], v[62:63] op_sel_hi:[1,0] neg_lo:[0,1] neg_hi:[0,1]
	v_pk_mul_f32 v[56:57], v[58:59], v[56:57]
	v_add_f32_e32 v59, 1.0, v64
	v_pk_mul_f32 v[64:65], v[54:55], v[54:55]
	v_pk_add_f32 v[52:53], v[52:53], v[62:63] op_sel_hi:[1,0] neg_lo:[0,1] neg_hi:[0,1]
	v_add_f32_e32 v47, v64, v65
	v_pk_mul_f32 v[66:67], v[52:53], v[52:53]
	v_pk_add_f32 v[68:69], v[44:45], v[62:63] op_sel_hi:[1,0] neg_lo:[0,1] neg_hi:[0,1]
	v_add_f32_e32 v47, v47, v66
	v_pk_mul_f32 v[44:45], v[68:69], v[68:69]
	v_add_f32_e32 v47, v47, v67
	v_add_f32_e32 v58, 1.0, v63
	v_pk_add_f32 v[62:63], v[42:43], v[62:63] op_sel_hi:[1,0] neg_lo:[0,1] neg_hi:[0,1]
	v_add_f32_e32 v44, v47, v44
	v_pk_mul_f32 v[42:43], v[62:63], v[62:63]
	v_add_f32_e32 v44, v44, v45
	v_add_f32_e32 v42, v44, v42
	v_add_f32_e32 v44, v42, v43
	ds_bpermute_b32 v45, v184, v44
	v_pk_mul_f32 v[42:43], v[46:47], v[50:51] op_sel_hi:[0,1]
	v_pk_fma_f32 v[42:43], v[42:43], v[28:29], v[32:33]
	v_rcp_f32_e32 v58, v58
	v_mul_f32_e32 v46, 0xbfb8aa3b, v42
	s_waitcnt lgkmcnt(0)
	v_add_f32_e32 v44, v44, v45
	ds_bpermute_b32 v45, v185, v44
	v_exp_f32_e32 v46, v46
	v_mul_f32_e32 v47, 0xbfb8aa3b, v43
	v_rcp_f32_e32 v59, v59
	v_exp_f32_e32 v47, v47
	s_waitcnt lgkmcnt(0)
	v_add_f32_e32 v50, v44, v45
	ds_bpermute_b32 v51, v186, v50
	v_add_f32_e32 v46, 1.0, v46
	v_rcp_f32_e32 v44, v46
	v_add_f32_e32 v45, 1.0, v47
	v_pk_mul_f32 v[46:47], v[60:61], v[58:59]
	s_waitcnt lgkmcnt(0)
	v_add_f32_e32 v58, v50, v51
	ds_bpermute_b32 v59, v187, v58
	v_rcp_f32_e32 v45, v45
	v_cvt_pk_f16_f32 v46, v46, v47
	v_pk_mul_f32 v[50:51], v[42:43], v[44:45]
	s_waitcnt lgkmcnt(0)
	v_add_f32_e32 v44, v58, v59
	ds_bpermute_b32 v45, v188, v44
	v_cvt_pk_f16_f32 v42, v48, v49
	v_cvt_pk_f16_f32 v43, v56, v57
	v_add_u32_e32 v42, 0x40004, v42
	v_add_u32_e32 v43, 0x40004, v43
	s_waitcnt lgkmcnt(0)
	v_add_f32_e32 v45, v44, v45
	ds_bpermute_b32 v47, v189, v45
	v_add_u32_e32 v44, 0x40004, v46
	v_cvt_pk_f16_f32 v46, v50, v51
	v_add_u32_e32 v48, 0x40004, v46
	v_and_b32_e32 v42, 0xfff8fff8, v42
	s_waitcnt lgkmcnt(0)
	v_add_f32_e32 v45, v45, v47
	v_fmamk_f32 v45, v45, 0x3b000000, v207
	v_rsq_f32_e32 v46, v45
	v_and_b32_e32 v45, 0xfff8fff8, v48
	v_and_b32_e32 v43, 0xfff8fff8, v43
	v_and_b32_e32 v44, 0xfff8fff8, v44
	v_pk_mul_f32 v[48:49], v[46:47], v[54:55] op_sel_hi:[0,1]
	v_pk_add_f32 v[54:55], v[18:19], v[148:149]
	v_lshl_add_u64 v[50:51], v[104:105], 0, s[8:9]
	v_add_f32_e32 v56, 0, v54
	global_store_dwordx4 v[50:51], v[42:45], off
	v_pk_add_f32 v[50:51], v[20:21], v[146:147]
	v_add_f32_e32 v56, v56, v55
	v_add_f32_e32 v56, v56, v50
	v_pk_fma_f32 v[48:49], v[48:49], v[34:35], v[38:39]
	v_pk_add_f32 v[44:45], v[22:23], v[144:145]
	v_add_f32_e32 v56, v56, v51
	v_mul_f32_e32 v42, 0xbfb8aa3b, v49
	v_add_f32_e32 v56, v56, v44
	v_exp_f32_e32 v57, v42
	v_pk_add_f32 v[42:43], v[24:25], v[142:143]
	v_add_f32_e32 v56, v56, v45
	v_mul_f32_e32 v47, 0xbfb8aa3b, v48
	v_add_f32_e32 v56, v56, v42
	v_exp_f32_e32 v47, v47
	v_add_f32_e32 v58, v56, v43
	ds_bpermute_b32 v59, v184, v58
	s_or_b32 s8, s0, 3
	v_add_f32_e32 v47, 1.0, v47
	v_rcp_f32_e32 v56, v47
	v_add_f32_e32 v47, 1.0, v57
	v_rcp_f32_e32 v57, v47
	v_pk_mul_f32 v[52:53], v[46:47], v[52:53] op_sel_hi:[0,1]
	s_waitcnt lgkmcnt(0)
; __device__ __forceinline__ unsigned pkh8(float lo, float hi) { return rnd8a(pkh(lo, hi)); }
; __device__ __forceinline__ float sigmoidf_(float x) { return __builtin_amdgcn_rcpf(1.0f + __builtin_amdgcn_exp2f(-x * LOG2E)); }
; __global__ void __launch_bounds__(NWAVES * 64, 2) fwd_kernel(Args args) {
;     ...
;                 for (int i = 0; i < 8; ++i) { float s_ = 0.f;
; #pragma unroll
;                     for (int e = 0; e < 8; ++e) { acc[i][e] += cb[e]; s_ += acc[i][e]; }
;                     sm[i] = s_; }
;                 wave_sum_n<8>(sm);
; #pragma unroll
;                 for (int i = 0; i < 8; ++i) { const float mu = sm[i] * (1.0f / CONV_CH); sm[i] = mu; float q_ = 0.f;
; #pragma unroll
;                     for (int e = 0; e < 8; ++e) { acc[i][e] -= mu; q_ += acc[i][e] * acc[i][e]; }
;                     sq[i] = q_; }
;                 wave_sum_n<8>(sq);
; #pragma unroll
;                 for (int i = 0; i < 8; ++i) {
;                     const float rstd = __builtin_amdgcn_rsqf(sq[i] * (1.0f / CONV_CH) + EPS);
;                     float y[8];
; #pragma unroll
;                     for (int e = 0; e < 8; ++e) { const float z = acc[i][e] * rstd * gam[e] + bet[e]; y[e] = z * sigmoidf_(z); }
;                     u32x4 w; w.x = pkh8(y[0], y[1]); w.y = pkh8(y[2], y[3]); w.z = pkh8(y[4], y[5]); w.w = pkh8(y[6], y[7]);
;                     *(u32x4*)(MIX + (size_t)(t0 + wave * 8 + i) * D + c0) = w;
	v_add_f32_e32 v47, v58, v59
	ds_bpermute_b32 v58, v185, v47
	v_pk_mul_f32 v[48:49], v[48:49], v[56:57]
	v_pk_fma_f32 v[52:53], v[52:53], v[36:37], v[40:41]
	s_ashr_i32 s9, s8, 31
	v_mul_f32_e32 v59, 0xbfb8aa3b, v52
	s_waitcnt lgkmcnt(0)
	v_add_f32_e32 v47, v47, v58
	ds_bpermute_b32 v57, v186, v47
	v_mul_f32_e32 v58, 0xbfb8aa3b, v53
	v_exp_f32_e32 v59, v59
	v_exp_f32_e32 v58, v58
	s_lshl_b64 s[8:9], s[8:9], 11
	s_waitcnt lgkmcnt(0)
	v_add_f32_e32 v47, v47, v57
	ds_bpermute_b32 v60, v187, v47
	v_add_f32_e32 v56, 1.0, v59
	v_add_f32_e32 v57, 1.0, v58
	v_pk_mul_f32 v[58:59], v[46:47], v[68:69] op_sel_hi:[0,1]
	v_pk_fma_f32 v[58:59], v[58:59], v[26:27], v[30:31]
	s_waitcnt lgkmcnt(0)
	v_add_f32_e32 v47, v47, v60
	ds_bpermute_b32 v60, v188, v47
	v_mul_f32_e32 v61, 0xbfb8aa3b, v58
	v_exp_f32_e32 v61, v61
	v_mul_f32_e32 v64, 0xbfb8aa3b, v59
	v_rcp_f32_e32 v56, v56
	s_waitcnt lgkmcnt(0)
	v_add_f32_e32 v47, v47, v60
	ds_bpermute_b32 v60, v189, v47
	v_rcp_f32_e32 v57, v57
	v_exp_f32_e32 v64, v64
	s_waitcnt lgkmcnt(0)
	v_add_f32_e32 v47, v47, v60
	v_mul_f32_e32 v60, 0x3b000000, v47
	v_pk_add_f32 v[54:55], v[54:55], v[60:61] op_sel_hi:[1,0] neg_lo:[0,1] neg_hi:[0,1]
	v_pk_mul_f32 v[52:53], v[52:53], v[56:57]
	v_add_f32_e32 v57, 1.0, v64
	v_pk_mul_f32 v[64:65], v[54:55], v[54:55]
	v_pk_add_f32 v[50:51], v[50:51], v[60:61] op_sel_hi:[1,0] neg_lo:[0,1] neg_hi:[0,1]
	v_add_f32_e32 v47, v64, v65
	v_pk_mul_f32 v[66:67], v[50:51], v[50:51]
	v_pk_add_f32 v[68:69], v[44:45], v[60:61] op_sel_hi:[1,0] neg_lo:[0,1] neg_hi:[0,1]
	v_add_f32_e32 v47, v47, v66
	v_pk_mul_f32 v[44:45], v[68:69], v[68:69]
	v_add_f32_e32 v47, v47, v67
	v_add_f32_e32 v56, 1.0, v61
	v_pk_add_f32 v[60:61], v[42:43], v[60:61] op_sel_hi:[1,0] neg_lo:[0,1] neg_hi:[0,1]
	v_add_f32_e32 v44, v47, v44
	v_pk_mul_f32 v[42:43], v[60:61], v[60:61]
	v_add_f32_e32 v44, v44, v45
	v_add_f32_e32 v42, v44, v42
	v_add_f32_e32 v44, v42, v43
	ds_bpermute_b32 v45, v184, v44
	v_pk_mul_f32 v[42:43], v[46:47], v[62:63] op_sel_hi:[0,1]
	v_pk_fma_f32 v[42:43], v[42:43], v[28:29], v[32:33]
	v_rcp_f32_e32 v56, v56
	v_mul_f32_e32 v46, 0xbfb8aa3b, v42
	s_waitcnt lgkmcnt(0)
	v_add_f32_e32 v44, v44, v45
	ds_bpermute_b32 v45, v185, v44
	v_exp_f32_e32 v46, v46
	v_mul_f32_e32 v47, 0xbfb8aa3b, v43
	v_rcp_f32_e32 v57, v57
	v_exp_f32_e32 v47, v47
	s_waitcnt lgkmcnt(0)
	v_add_f32_e32 v62, v44, v45
	ds_bpermute_b32 v63, v186, v62
	v_add_f32_e32 v46, 1.0, v46
	v_rcp_f32_e32 v44, v46
	v_add_f32_e32 v45, 1.0, v47
	v_pk_mul_f32 v[46:47], v[58:59], v[56:57]
	s_waitcnt lgkmcnt(0)
	v_add_f32_e32 v58, v62, v63
	ds_bpermute_b32 v59, v187, v58
	v_rcp_f32_e32 v45, v45
	v_cvt_pk_f16_f32 v46, v46, v47
	v_pk_mul_f32 v[56:57], v[42:43], v[44:45]
	s_waitcnt lgkmcnt(0)
	v_add_f32_e32 v44, v58, v59
	ds_bpermute_b32 v45, v188, v44
	v_cvt_pk_f16_f32 v42, v48, v49
	v_cvt_pk_f16_f32 v43, v52, v53
	v_add_u32_e32 v42, 0x40004, v42
	v_add_u32_e32 v43, 0x40004, v43
	s_waitcnt lgkmcnt(0)
	v_add_f32_e32 v45, v44, v45
	ds_bpermute_b32 v47, v189, v45
	v_add_u32_e32 v44, 0x40004, v46
	v_cvt_pk_f16_f32 v46, v56, v57
	v_add_u32_e32 v48, 0x40004, v46
	v_and_b32_e32 v42, 0xfff8fff8, v42
	s_waitcnt lgkmcnt(0)
	v_add_f32_e32 v45, v45, v47
	v_fmamk_f32 v45, v45, 0x3b000000, v207
	v_rsq_f32_e32 v46, v45
	v_and_b32_e32 v45, 0xfff8fff8, v48
	v_and_b32_e32 v43, 0xfff8fff8, v43
	v_and_b32_e32 v44, 0xfff8fff8, v44
	v_pk_mul_f32 v[48:49], v[46:47], v[54:55] op_sel_hi:[0,1]
	v_pk_add_f32 v[54:55], v[18:19], v[140:141]
	v_lshl_add_u64 v[52:53], v[104:105], 0, s[8:9]
	v_add_f32_e32 v56, 0, v54
	global_store_dwordx4 v[52:53], v[42:45], off
	v_pk_add_f32 v[52:53], v[20:21], v[138:139]
	v_add_f32_e32 v56, v56, v55
	v_add_f32_e32 v56, v56, v52
	v_pk_fma_f32 v[48:49], v[48:49], v[34:35], v[38:39]
	v_pk_add_f32 v[44:45], v[22:23], v[136:137]
	v_add_f32_e32 v56, v56, v53
	v_mul_f32_e32 v42, 0xbfb8aa3b, v49
	v_add_f32_e32 v56, v56, v44
	v_exp_f32_e32 v57, v42
	v_pk_add_f32 v[42:43], v[24:25], v[134:135]
	v_add_f32_e32 v56, v56, v45
	v_mul_f32_e32 v47, 0xbfb8aa3b, v48
	v_add_f32_e32 v56, v56, v42
	v_exp_f32_e32 v47, v47
	v_add_f32_e32 v58, v56, v43
	ds_bpermute_b32 v59, v184, v58
	s_or_b32 s8, s0, 4
	v_add_f32_e32 v47, 1.0, v47
	v_rcp_f32_e32 v56, v47
	v_add_f32_e32 v47, 1.0, v57
	v_rcp_f32_e32 v57, v47
	v_pk_mul_f32 v[50:51], v[46:47], v[50:51] op_sel_hi:[0,1]
	s_waitcnt lgkmcnt(0)
	v_add_f32_e32 v47, v58, v59
	ds_bpermute_b32 v58, v185, v47
	v_pk_mul_f32 v[48:49], v[48:49], v[56:57]
	v_pk_fma_f32 v[50:51], v[50:51], v[36:37], v[40:41]
	s_ashr_i32 s9, s8, 31
	v_mul_f32_e32 v59, 0xbfb8aa3b, v50
	s_waitcnt lgkmcnt(0)
	v_add_f32_e32 v47, v47, v58
	ds_bpermute_b32 v57, v186, v47
	v_mul_f32_e32 v58, 0xbfb8aa3b, v51
	v_exp_f32_e32 v59, v59
	v_exp_f32_e32 v58, v58
	s_lshl_b64 s[8:9], s[8:9], 11
	s_waitcnt lgkmcnt(0)
	v_add_f32_e32 v47, v47, v57
	ds_bpermute_b32 v62, v187, v47
	v_add_f32_e32 v56, 1.0, v59
	v_add_f32_e32 v57, 1.0, v58
	v_pk_mul_f32 v[58:59], v[46:47], v[68:69] op_sel_hi:[0,1]
	v_pk_fma_f32 v[58:59], v[58:59], v[26:27], v[30:31]
	s_waitcnt lgkmcnt(0)
	v_add_f32_e32 v47, v47, v62
	ds_bpermute_b32 v62, v188, v47
	v_mul_f32_e32 v63, 0xbfb8aa3b, v58
	v_exp_f32_e32 v63, v63
	v_mul_f32_e32 v64, 0xbfb8aa3b, v59
	v_rcp_f32_e32 v56, v56
	s_waitcnt lgkmcnt(0)
	v_add_f32_e32 v47, v47, v62
	ds_bpermute_b32 v62, v189, v47
	v_rcp_f32_e32 v57, v57
	v_exp_f32_e32 v64, v64
	s_waitcnt lgkmcnt(0)
; __device__ __forceinline__ unsigned pkh8(float lo, float hi) { return rnd8a(pkh(lo, hi)); }
; __device__ __forceinline__ float sigmoidf_(float x) { return __builtin_amdgcn_rcpf(1.0f + __builtin_amdgcn_exp2f(-x * LOG2E)); }
; __global__ void __launch_bounds__(NWAVES * 64, 2) fwd_kernel(Args args) {
;     ...
;                 for (int i = 0; i < 8; ++i) { float s_ = 0.f;
; #pragma unroll
;                     for (int e = 0; e < 8; ++e) { acc[i][e] += cb[e]; s_ += acc[i][e]; }
;                     sm[i] = s_; }
;                 wave_sum_n<8>(sm);
; #pragma unroll
;                 for (int i = 0; i < 8; ++i) { const float mu = sm[i] * (1.0f / CONV_CH); sm[i] = mu; float q_ = 0.f;
; #pragma unroll
;                     for (int e = 0; e < 8; ++e) { acc[i][e] -= mu; q_ += acc[i][e] * acc[i][e]; }
;                     sq[i] = q_; }
;                 wave_sum_n<8>(sq);
; #pragma unroll
;                 for (int i = 0; i < 8; ++i) {
;                     const float rstd = __builtin_amdgcn_rsqf(sq[i] * (1.0f / CONV_CH) + EPS);
;                     float y[8];
; #pragma unroll
;                     for (int e = 0; e < 8; ++e) { const float z = acc[i][e] * rstd * gam[e] + bet[e]; y[e] = z * sigmoidf_(z); }
;                     u32x4 w; w.x = pkh8(y[0], y[1]); w.y = pkh8(y[2], y[3]); w.z = pkh8(y[4], y[5]); w.w = pkh8(y[6], y[7]);
;                     *(u32x4*)(MIX + (size_t)(t0 + wave * 8 + i) * D + c0) = w;
	v_add_f32_e32 v47, v47, v62
	v_mul_f32_e32 v62, 0x3b000000, v47
	v_pk_add_f32 v[54:55], v[54:55], v[62:63] op_sel_hi:[1,0] neg_lo:[0,1] neg_hi:[0,1]
	v_pk_mul_f32 v[50:51], v[50:51], v[56:57]
	v_add_f32_e32 v57, 1.0, v64
	v_pk_mul_f32 v[64:65], v[54:55], v[54:55]
	v_pk_add_f32 v[52:53], v[52:53], v[62:63] op_sel_hi:[1,0] neg_lo:[0,1] neg_hi:[0,1]
	v_add_f32_e32 v47, v64, v65
	v_pk_mul_f32 v[66:67], v[52:53], v[52:53]
	v_pk_add_f32 v[68:69], v[44:45], v[62:63] op_sel_hi:[1,0] neg_lo:[0,1] neg_hi:[0,1]
	v_add_f32_e32 v47, v47, v66
	v_pk_mul_f32 v[44:45], v[68:69], v[68:69]
	v_add_f32_e32 v47, v47, v67
	v_add_f32_e32 v56, 1.0, v63
	v_pk_add_f32 v[62:63], v[42:43], v[62:63] op_sel_hi:[1,0] neg_lo:[0,1] neg_hi:[0,1]
	v_add_f32_e32 v44, v47, v44
	v_pk_mul_f32 v[42:43], v[62:63], v[62:63]
	v_add_f32_e32 v44, v44, v45
	v_add_f32_e32 v42, v44, v42
	v_add_f32_e32 v44, v42, v43
	ds_bpermute_b32 v45, v184, v44
	v_pk_mul_f32 v[42:43], v[46:47], v[60:61] op_sel_hi:[0,1]
	v_pk_fma_f32 v[42:43], v[42:43], v[28:29], v[32:33]
	v_rcp_f32_e32 v56, v56
	v_mul_f32_e32 v46, 0xbfb8aa3b, v42
	s_waitcnt lgkmcnt(0)
	v_add_f32_e32 v44, v44, v45
	ds_bpermute_b32 v45, v185, v44
	v_exp_f32_e32 v46, v46
	v_mul_f32_e32 v47, 0xbfb8aa3b, v43
	v_rcp_f32_e32 v57, v57
	v_exp_f32_e32 v47, v47
	s_waitcnt lgkmcnt(0)
	v_add_f32_e32 v60, v44, v45
	ds_bpermute_b32 v61, v186, v60
	v_add_f32_e32 v46, 1.0, v46
	v_rcp_f32_e32 v44, v46
	v_add_f32_e32 v45, 1.0, v47
	v_pk_mul_f32 v[46:47], v[58:59], v[56:57]
	s_waitcnt lgkmcnt(0)
	v_add_f32_e32 v58, v60, v61
	ds_bpermute_b32 v59, v187, v58
	v_rcp_f32_e32 v45, v45
	v_cvt_pk_f16_f32 v46, v46, v47
	v_pk_mul_f32 v[56:57], v[42:43], v[44:45]
	s_waitcnt lgkmcnt(0)
	v_add_f32_e32 v44, v58, v59
	ds_bpermute_b32 v45, v188, v44
	v_cvt_pk_f16_f32 v42, v48, v49
	v_cvt_pk_f16_f32 v43, v50, v51
	v_add_u32_e32 v42, 0x40004, v42
	v_add_u32_e32 v43, 0x40004, v43
	s_waitcnt lgkmcnt(0)
	v_add_f32_e32 v45, v44, v45
	ds_bpermute_b32 v47, v189, v45
	v_add_u32_e32 v44, 0x40004, v46
	v_cvt_pk_f16_f32 v46, v56, v57
	v_add_u32_e32 v48, 0x40004, v46
	v_and_b32_e32 v42, 0xfff8fff8, v42
	s_waitcnt lgkmcnt(0)
	v_add_f32_e32 v45, v45, v47
	v_fmamk_f32 v45, v45, 0x3b000000, v207
	v_rsq_f32_e32 v46, v45
	v_and_b32_e32 v45, 0xfff8fff8, v48
	v_and_b32_e32 v43, 0xfff8fff8, v43
	v_and_b32_e32 v44, 0xfff8fff8, v44
	v_pk_mul_f32 v[48:49], v[46:47], v[54:55] op_sel_hi:[0,1]
	v_pk_fma_f32 v[48:49], v[48:49], v[34:35], v[38:39]
	v_lshl_add_u64 v[50:51], v[104:105], 0, s[8:9]
	v_mul_f32_e32 v47, 0xbfb8aa3b, v48
	v_exp_f32_e32 v47, v47
	v_pk_add_f32 v[56:57], v[18:19], v[132:133]
	global_store_dwordx4 v[50:51], v[42:45], off
	v_pk_add_f32 v[54:55], v[20:21], v[130:131]
	v_pk_add_f32 v[50:51], v[22:23], v[128:129]
	v_add_f32_e32 v42, 1.0, v47
	v_add_f32_e32 v47, 0, v56
	v_add_f32_e32 v47, v47, v57
	v_add_f32_e32 v47, v47, v54
	v_add_f32_e32 v47, v47, v55
	v_add_f32_e32 v47, v47, v50
	v_pk_add_f32 v[44:45], v[24:25], v[126:127]
	v_add_f32_e32 v47, v47, v51
	v_add_f32_e32 v47, v47, v44
	v_add_f32_e32 v47, v47, v45
	ds_bpermute_b32 v58, v184, v47
	v_pk_mul_f32 v[52:53], v[46:47], v[52:53] op_sel_hi:[0,1]
	v_pk_fma_f32 v[52:53], v[52:53], v[36:37], v[40:41]
	v_mul_f32_e32 v43, 0xbfb8aa3b, v49
	v_mul_f32_e32 v59, 0xbfb8aa3b, v52
	s_waitcnt lgkmcnt(0)
	v_add_f32_e32 v47, v47, v58
	ds_bpermute_b32 v58, v185, v47
	v_mul_f32_e32 v60, 0xbfb8aa3b, v53
	v_exp_f32_e32 v59, v59
	v_exp_f32_e32 v60, v60
	v_exp_f32_e32 v43, v43
	s_waitcnt lgkmcnt(0)
	v_add_f32_e32 v47, v47, v58
	ds_bpermute_b32 v64, v186, v47
	v_add_f32_e32 v58, 1.0, v59
	v_add_f32_e32 v59, 1.0, v60
	v_pk_mul_f32 v[60:61], v[46:47], v[68:69] op_sel_hi:[0,1]
	v_pk_fma_f32 v[60:61], v[60:61], v[26:27], v[30:31]
	s_waitcnt lgkmcnt(0)
	v_add_f32_e32 v47, v47, v64
	ds_bpermute_b32 v64, v187, v47
	v_mul_f32_e32 v65, 0xbfb8aa3b, v60
	v_exp_f32_e32 v65, v65
	v_add_f32_e32 v43, 1.0, v43
	v_rcp_f32_e32 v42, v42
	s_waitcnt lgkmcnt(0)
	v_add_f32_e32 v47, v47, v64
	ds_bpermute_b32 v66, v188, v47
	v_add_f32_e32 v64, 1.0, v65
	v_mul_f32_e32 v65, 0xbfb8aa3b, v61
	v_exp_f32_e32 v65, v65
	v_rcp_f32_e32 v43, v43
	s_waitcnt lgkmcnt(0)
	v_add_f32_e32 v66, v47, v66
	ds_bpermute_b32 v67, v189, v66
	v_add_f32_e32 v47, 1.0, v65
	v_rcp_f32_e32 v65, v47
	v_pk_mul_f32 v[46:47], v[46:47], v[62:63] op_sel_hi:[0,1]
	v_pk_fma_f32 v[46:47], v[46:47], v[28:29], v[32:33]
	s_waitcnt lgkmcnt(0)
	v_add_f32_e32 v62, v66, v67
	v_mul_f32_e32 v62, 0x3b000000, v62
	v_pk_add_f32 v[56:57], v[56:57], v[62:63] op_sel_hi:[1,0] neg_lo:[0,1] neg_hi:[0,1]
	v_pk_add_f32 v[54:55], v[54:55], v[62:63] op_sel_hi:[1,0] neg_lo:[0,1] neg_hi:[0,1]
	v_pk_mul_f32 v[66:67], v[56:57], v[56:57]
	v_pk_mul_f32 v[68:69], v[54:55], v[54:55]
	v_add_f32_e32 v66, v66, v67
	v_pk_add_f32 v[50:51], v[50:51], v[62:63] op_sel_hi:[1,0] neg_lo:[0,1] neg_hi:[0,1]
	v_add_f32_e32 v66, v66, v68
	v_pk_mul_f32 v[70:71], v[50:51], v[50:51]
	v_add_f32_e32 v66, v66, v69
	v_pk_add_f32 v[62:63], v[44:45], v[62:63] op_sel_hi:[1,0] neg_lo:[0,1] neg_hi:[0,1]
	v_add_f32_e32 v66, v66, v70
	v_pk_mul_f32 v[44:45], v[62:63], v[62:63]
	v_add_f32_e32 v66, v66, v71
	v_add_f32_e32 v44, v66, v44
	v_add_f32_e32 v44, v44, v45
	ds_bpermute_b32 v45, v184, v44
	v_mul_f32_e32 v66, 0xbfb8aa3b, v46
	v_exp_f32_e32 v66, v66
	v_mul_f32_e32 v67, 0xbfb8aa3b, v47
	v_exp_f32_e32 v67, v67
	s_waitcnt lgkmcnt(0)
	v_add_f32_e32 v68, v44, v45
	ds_bpermute_b32 v69, v185, v68
	v_add_f32_e32 v44, 1.0, v66
	v_add_f32_e32 v45, 1.0, v67
	v_rcp_f32_e32 v44, v44
	v_rcp_f32_e32 v45, v45
	s_waitcnt lgkmcnt(0)
	v_add_f32_e32 v66, v68, v69
	ds_bpermute_b32 v67, v186, v66
	v_rcp_f32_e32 v58, v58
	v_pk_mul_f32 v[46:47], v[46:47], v[44:45]
	v_rcp_f32_e32 v59, v59
	v_rcp_f32_e32 v64, v64
	s_waitcnt lgkmcnt(0)
; __device__ __forceinline__ unsigned pkh8(float lo, float hi) { return rnd8a(pkh(lo, hi)); }
; __device__ __forceinline__ float sigmoidf_(float x) { return __builtin_amdgcn_rcpf(1.0f + __builtin_amdgcn_exp2f(-x * LOG2E)); }
; __global__ void __launch_bounds__(NWAVES * 64, 2) fwd_kernel(Args args) {
;     ...
;                 for (int i = 0; i < 8; ++i) { float s_ = 0.f;
; #pragma unroll
;                     for (int e = 0; e < 8; ++e) { acc[i][e] += cb[e]; s_ += acc[i][e]; }
;                     sm[i] = s_; }
;                 wave_sum_n<8>(sm);
; #pragma unroll
;                 for (int i = 0; i < 8; ++i) { const float mu = sm[i] * (1.0f / CONV_CH); sm[i] = mu; float q_ = 0.f;
; #pragma unroll
;                     for (int e = 0; e < 8; ++e) { acc[i][e] -= mu; q_ += acc[i][e] * acc[i][e]; }
;                     sq[i] = q_; }
;                 wave_sum_n<8>(sq);
; #pragma unroll
;                 for (int i = 0; i < 8; ++i) {
;                     const float rstd = __builtin_amdgcn_rsqf(sq[i] * (1.0f / CONV_CH) + EPS);
;                     float y[8];
; #pragma unroll
;                     for (int e = 0; e < 8; ++e) { const float z = acc[i][e] * rstd * gam[e] + bet[e]; y[e] = z * sigmoidf_(z); }
;                     u32x4 w; w.x = pkh8(y[0], y[1]); w.y = pkh8(y[2], y[3]); w.z = pkh8(y[4], y[5]); w.w = pkh8(y[6], y[7]);
;                     *(u32x4*)(MIX + (size_t)(t0 + wave * 8 + i) * D + c0) = w;
	v_add_f32_e32 v44, v66, v67
	ds_bpermute_b32 v45, v187, v44
	v_pk_mul_f32 v[42:43], v[48:49], v[42:43]
	v_pk_mul_f32 v[48:49], v[52:53], v[58:59]
	v_pk_mul_f32 v[52:53], v[60:61], v[64:65]
	v_cvt_pk_f16_f32 v42, v42, v43
	s_waitcnt lgkmcnt(0)
	v_add_f32_e32 v44, v44, v45
	ds_bpermute_b32 v45, v188, v44
	v_cvt_pk_f16_f32 v43, v48, v49
	v_cvt_pk_f16_f32 v48, v52, v53
	v_add_u32_e32 v48, 0x40004, v48
	v_pk_add_f32 v[18:19], v[18:19], v[124:125]
	s_waitcnt lgkmcnt(0)
	v_add_f32_e32 v49, v44, v45
	ds_bpermute_b32 v52, v189, v49
	v_cvt_pk_f16_f32 v45, v46, v47
	v_and_b32_e32 v44, 0xfff8fff8, v48
	v_pk_add_f32 v[20:21], v[20:21], v[122:123]
	v_pk_add_f32 v[22:23], v[22:23], v[120:121]
	s_waitcnt lgkmcnt(0)
	v_add_f32_e32 v46, v49, v52
	v_fmamk_f32 v46, v46, 0x3b000000, v207
	v_rsq_f32_e32 v46, v46
	v_pk_add_f32 v[24:25], v[24:25], v[118:119]
	s_or_b32 s8, s0, 5
	s_ashr_i32 s9, s8, 31
	v_pk_mul_f32 v[48:49], v[46:47], v[56:57] op_sel_hi:[0,1]
	v_pk_fma_f32 v[48:49], v[48:49], v[34:35], v[38:39]
	v_add_u32_e32 v42, 0x40004, v42
	v_mul_f32_e32 v47, 0xbfb8aa3b, v48
	v_exp_f32_e32 v47, v47
	v_mul_f32_e32 v52, 0xbfb8aa3b, v49
	v_exp_f32_e32 v57, v52
	v_add_u32_e32 v43, 0x40004, v43
	v_add_f32_e32 v47, 1.0, v47
	v_rcp_f32_e32 v56, v47
	v_add_f32_e32 v47, 1.0, v57
	v_rcp_f32_e32 v57, v47
	v_add_f32_e32 v47, 0, v18
	v_add_f32_e32 v47, v47, v19
	v_add_f32_e32 v47, v47, v20
	v_add_f32_e32 v47, v47, v21
	v_add_f32_e32 v47, v47, v22
	v_add_f32_e32 v47, v47, v23
	v_add_f32_e32 v47, v47, v24
	v_add_f32_e32 v47, v47, v25
	ds_bpermute_b32 v58, v184, v47
	v_add_u32_e32 v45, 0x40004, v45
	s_lshl_b64 s[8:9], s[8:9], 11
	v_and_b32_e32 v42, 0xfff8fff8, v42
	v_and_b32_e32 v43, 0xfff8fff8, v43
	v_and_b32_e32 v45, 0xfff8fff8, v45
	v_lshl_add_u64 v[52:53], v[104:105], 0, s[8:9]
	global_store_dwordx4 v[52:53], v[42:45], off
	s_or_b32 s8, s0, 6
	s_ashr_i32 s9, s8, 31
	v_pk_mul_f32 v[44:45], v[46:47], v[54:55] op_sel_hi:[0,1]
	s_waitcnt lgkmcnt(0)
	v_add_f32_e32 v47, v47, v58
	v_pk_mul_f32 v[42:43], v[48:49], v[56:57]
	ds_bpermute_b32 v48, v185, v47
	v_pk_fma_f32 v[44:45], v[44:45], v[36:37], v[40:41]
	s_lshl_b64 s[8:9], s[8:9], 11
	v_mul_f32_e32 v49, 0xbfb8aa3b, v44
	v_mul_f32_e32 v52, 0xbfb8aa3b, v45
	s_waitcnt lgkmcnt(0)
	v_add_f32_e32 v47, v47, v48
	ds_bpermute_b32 v53, v186, v47
	v_exp_f32_e32 v49, v49
	v_exp_f32_e32 v52, v52
	v_pk_mul_f32 v[50:51], v[46:47], v[50:51] op_sel_hi:[0,1]
	v_pk_fma_f32 v[50:51], v[50:51], v[26:27], v[30:31]
	s_waitcnt lgkmcnt(0)
	v_add_f32_e32 v47, v47, v53
	v_add_f32_e32 v48, 1.0, v49
	v_add_f32_e32 v49, 1.0, v52
	ds_bpermute_b32 v52, v187, v47
	v_mul_f32_e32 v53, 0xbfb8aa3b, v50
	v_exp_f32_e32 v53, v53
	v_rcp_f32_e32 v48, v48
	v_rcp_f32_e32 v49, v49
	s_waitcnt lgkmcnt(0)
	v_add_f32_e32 v47, v47, v52
	ds_bpermute_b32 v54, v188, v47
	v_add_f32_e32 v52, 1.0, v53
	v_mul_f32_e32 v53, 0xbfb8aa3b, v51
	v_exp_f32_e32 v53, v53
	v_rcp_f32_e32 v52, v52
	s_waitcnt lgkmcnt(0)
	v_add_f32_e32 v54, v47, v54
	ds_bpermute_b32 v55, v189, v54
	v_add_f32_e32 v47, 1.0, v53
	v_rcp_f32_e32 v53, v47
	v_pk_mul_f32 v[46:47], v[46:47], v[62:63] op_sel_hi:[0,1]
	v_pk_fma_f32 v[46:47], v[46:47], v[28:29], v[32:33]
	s_waitcnt lgkmcnt(0)
	v_add_f32_e32 v54, v54, v55
	v_mul_f32_e32 v54, 0x3b000000, v54
	v_pk_add_f32 v[56:57], v[18:19], v[54:55] op_sel_hi:[1,0] neg_lo:[0,1] neg_hi:[0,1]
	v_pk_add_f32 v[58:59], v[20:21], v[54:55] op_sel_hi:[1,0] neg_lo:[0,1] neg_hi:[0,1]
	v_pk_mul_f32 v[18:19], v[56:57], v[56:57]
	v_pk_mul_f32 v[20:21], v[58:59], v[58:59]
	v_add_f32_e32 v18, v18, v19
	v_pk_add_f32 v[22:23], v[22:23], v[54:55] op_sel_hi:[1,0] neg_lo:[0,1] neg_hi:[0,1]
	v_add_f32_e32 v18, v18, v20
	v_pk_mul_f32 v[60:61], v[22:23], v[22:23]
	v_add_f32_e32 v18, v18, v21
	v_pk_add_f32 v[24:25], v[24:25], v[54:55] op_sel_hi:[1,0] neg_lo:[0,1] neg_hi:[0,1]
	v_add_f32_e32 v18, v18, v60
	v_pk_mul_f32 v[54:55], v[24:25], v[24:25]
	v_add_f32_e32 v18, v18, v61
	v_add_f32_e32 v18, v18, v54
	v_add_f32_e32 v18, v18, v55
	ds_bpermute_b32 v19, v184, v18
	v_mul_f32_e32 v20, 0xbfb8aa3b, v46
	v_mul_f32_e32 v21, 0xbfb8aa3b, v47
	v_exp_f32_e32 v20, v20
	v_exp_f32_e32 v21, v21
	s_waitcnt lgkmcnt(0)
	v_add_f32_e32 v54, v18, v19
	ds_bpermute_b32 v55, v185, v54
	v_add_f32_e32 v18, 1.0, v20
	v_add_f32_e32 v19, 1.0, v21
	v_rcp_f32_e32 v18, v18
	v_rcp_f32_e32 v19, v19
	s_waitcnt lgkmcnt(0)
	v_add_f32_e32 v54, v54, v55
	ds_bpermute_b32 v55, v186, v54
	v_pk_mul_f32 v[20:21], v[44:45], v[48:49]
	v_pk_mul_f32 v[46:47], v[46:47], v[18:19]
	v_cvt_pk_f16_f32 v18, v42, v43
	v_cvt_pk_f16_f32 v20, v20, v21
	s_waitcnt lgkmcnt(0)
	v_add_f32_e32 v19, v54, v55
	ds_bpermute_b32 v42, v187, v19
	v_pk_mul_f32 v[44:45], v[50:51], v[52:53]
	v_add_u32_e32 v20, 0x40004, v20
	v_add_u32_e32 v18, 0x40004, v18
	v_and_b32_e32 v18, 0xfff8fff8, v18
	s_waitcnt lgkmcnt(0)
	v_add_f32_e32 v21, v19, v42
	ds_bpermute_b32 v42, v188, v21
	v_and_b32_e32 v19, 0xfff8fff8, v20
	v_cvt_pk_f16_f32 v20, v44, v45
	v_add_u32_e32 v20, 0x40004, v20
	v_and_b32_e32 v20, 0xfff8fff8, v20
	s_waitcnt lgkmcnt(0)
	v_add_f32_e32 v42, v21, v42
	ds_bpermute_b32 v43, v189, v42
	v_cvt_pk_f16_f32 v21, v46, v47
	v_add_u32_e32 v21, 0x40004, v21
	v_and_b32_e32 v21, 0xfff8fff8, v21
	v_lshl_add_u64 v[44:45], v[104:105], 0, s[8:9]
	s_waitcnt lgkmcnt(0)
; __device__ __forceinline__ unsigned pkh8(float lo, float hi) { return rnd8a(pkh(lo, hi)); }
; __device__ __forceinline__ float sigmoidf_(float x) { return __builtin_amdgcn_rcpf(1.0f + __builtin_amdgcn_exp2f(-x * LOG2E)); }
; __global__ void __launch_bounds__(NWAVES * 64, 2) fwd_kernel(Args args) {
;     ...
;                 for (int i = 0; i < 8; ++i) {
;                     const float rstd = __builtin_amdgcn_rsqf(sq[i] * (1.0f / CONV_CH) + EPS);
;                     float y[8];
; #pragma unroll
;                     for (int e = 0; e < 8; ++e) { const float z = acc[i][e] * rstd * gam[e] + bet[e]; y[e] = z * sigmoidf_(z); }
;                     u32x4 w; w.x = pkh8(y[0], y[1]); w.y = pkh8(y[2], y[3]); w.z = pkh8(y[4], y[5]); w.w = pkh8(y[6], y[7]);
;                     *(u32x4*)(MIX + (size_t)(t0 + wave * 8 + i) * D + c0) = w;
;                 }
;     ...
;             __syncthreads();
;         }
;     ...
;         if (G == 256 && !dry) {
;             int tl_ = threadIdx.x; asm volatile("" : "+v"(tl_));
;             const int wk = vcu * 512 + tl_, nwk = G * 512;
;         { const size_t n8 = (size_t)M * PLE / 8, stride = (size_t)nwk;
;           for (size_t i = (size_t)wk; i < n8; i += 4 * stride) {
;             f32x4 a[4], b[4];
; #pragma unroll
;             for (int q = 0; q < 4; ++q) { const size_t ii = (i + q * stride < n8) ? i + q * stride : n8 - 1; a[q] = __builtin_nontemporal_load((const f32x4*)p + 2 * ii); b[q] = __builtin_nontemporal_load((const f32x4*)p + 2 * ii + 1); }
; #pragma unroll
;             for (int q = 0; q < 4; ++q) if (i + q * stride < n8) { u32x4 w; w.x = pkh8(a[q][0], a[q][1]); w.y = pkh8(a[q][2], a[q][3]); w.z = pkh8(b[q][0], b[q][1]); w.w = pkh8(b[q][2], b[q][3]);
;                 *((u32x4*)P16 + i + q * stride) = w; }
;           } }
	v_add_f32_e32 v42, v42, v43
	v_fmamk_f32 v42, v42, 0x3b000000, v207
	v_rsq_f32_e32 v42, v42
	global_store_dwordx4 v[44:45], v[18:21], off
	s_or_b32 s0, s0, 7
	s_ashr_i32 s1, s0, 31
	v_pk_mul_f32 v[46:47], v[42:43], v[56:57] op_sel_hi:[0,1]
	v_pk_mul_f32 v[20:21], v[42:43], v[58:59] op_sel_hi:[0,1]
	v_pk_mul_f32 v[22:23], v[42:43], v[22:23] op_sel_hi:[0,1]
	v_pk_mul_f32 v[24:25], v[42:43], v[24:25] op_sel_hi:[0,1]
	v_pk_fma_f32 v[34:35], v[46:47], v[34:35], v[38:39]
	v_pk_fma_f32 v[20:21], v[20:21], v[36:37], v[40:41]
	v_pk_fma_f32 v[22:23], v[22:23], v[26:27], v[30:31]
	v_pk_fma_f32 v[24:25], v[24:25], v[28:29], v[32:33]
	v_mul_f32_e32 v38, 0xbfb8aa3b, v34
	v_mul_f32_e32 v39, 0xbfb8aa3b, v35
	v_mul_f32_e32 v36, 0xbfb8aa3b, v20
	v_mul_f32_e32 v37, 0xbfb8aa3b, v21
	v_mul_f32_e32 v26, 0xbfb8aa3b, v22
	v_mul_f32_e32 v27, 0xbfb8aa3b, v23
	v_mul_f32_e32 v28, 0xbfb8aa3b, v24
	v_mul_f32_e32 v29, 0xbfb8aa3b, v25
	v_exp_f32_e32 v38, v38
	v_exp_f32_e32 v39, v39
	v_exp_f32_e32 v36, v36
	v_exp_f32_e32 v37, v37
	v_exp_f32_e32 v26, v26
	v_exp_f32_e32 v27, v27
	v_exp_f32_e32 v28, v28
	v_exp_f32_e32 v29, v29
	v_add_f32_e32 v18, 1.0, v38
	v_add_f32_e32 v19, 1.0, v39
	v_add_f32_e32 v36, 1.0, v36
	v_add_f32_e32 v37, 1.0, v37
	v_add_f32_e32 v26, 1.0, v26
	v_add_f32_e32 v27, 1.0, v27
	v_add_f32_e32 v28, 1.0, v28
	v_add_f32_e32 v29, 1.0, v29
	v_rcp_f32_e32 v18, v18
	v_rcp_f32_e32 v19, v19
	v_rcp_f32_e32 v36, v36
	v_rcp_f32_e32 v37, v37
	v_rcp_f32_e32 v26, v26
	v_rcp_f32_e32 v27, v27
	v_rcp_f32_e32 v28, v28
	v_rcp_f32_e32 v29, v29
	v_pk_mul_f32 v[18:19], v[34:35], v[18:19]
	v_pk_mul_f32 v[20:21], v[20:21], v[36:37]
	v_pk_mul_f32 v[22:23], v[22:23], v[26:27]
	v_pk_mul_f32 v[24:25], v[24:25], v[28:29]
	v_cvt_pk_f16_f32 v18, v18, v19
	v_cvt_pk_f16_f32 v19, v20, v21
	v_cvt_pk_f16_f32 v20, v22, v23
	v_cvt_pk_f16_f32 v21, v24, v25
	v_add_u32_e32 v18, 0x40004, v18
	v_add_u32_e32 v19, 0x40004, v19
	v_add_u32_e32 v20, 0x40004, v20
	v_add_u32_e32 v21, 0x40004, v21
	s_lshl_b64 s[0:1], s[0:1], 11
	v_and_b32_e32 v18, 0xfff8fff8, v18
	v_and_b32_e32 v19, 0xfff8fff8, v19
	v_and_b32_e32 v20, 0xfff8fff8, v20
	v_and_b32_e32 v21, 0xfff8fff8, v21
	v_lshl_add_u64 v[22:23], v[104:105], 0, s[0:1]
	s_cmpk_gt_i32 s11, 0xff
	s_mov_b64 s[0:1], 0
	global_store_dwordx4 v[22:23], v[18:21], off
	s_cbranch_scc0 .LBB0_627
.LBB0_650:
	s_cmpk_lg_i32 s69, 0x100
	s_cselect_b64 s[0:1], -1, 0
	s_or_b64 s[0:1], s[0:1], s[66:67]
	s_andn2_b64 vcc, exec, s[0:1]
	s_waitcnt lgkmcnt(0)
	s_barrier
	s_cbranch_vccz .LBB0_659
	v_mov_b32_e32 v1, v0
	s_mov_b32 s0, 0x80000
	v_lshl_add_u32 v26, s85, 9, v1
	v_cmp_gt_u32_e32 vcc, s0, v26
	s_and_saveexec_b64 s[0:1], vcc
	s_cbranch_execz .LBB0_658
	v_mov_b32_e32 v27, 0
	v_readlane_b32 s2, v254, 42
	v_readlane_b32 s3, v254, 43
	s_waitcnt vmcnt(8)
	v_mov_b64_e32 v[34:35], v[210:211]
	v_mov_b64_e32 v[36:37], v[212:213]
	v_mov_b64_e32 v[30:31], v[214:215]
	v_mov_b64_e32 v[32:33], v[216:217]
	v_mov_b64_e32 v[18:19], v[218:219]
	v_mov_b64_e32 v[20:21], v[220:221]
	v_mov_b64_e32 v[10:11], v[222:223]
	v_mov_b64_e32 v[12:13], v[224:225]
	v_mov_b64_e32 v[22:23], v[226:227]
	v_mov_b64_e32 v[24:25], v[228:229]
	v_mov_b64_e32 v[14:15], v[230:231]
	v_mov_b64_e32 v[16:17], v[232:233]
	v_mov_b64_e32 v[6:7], v[234:235]
	v_mov_b64_e32 v[8:9], v[236:237]
	v_mov_b64_e32 v[2:3], v[238:239]
	v_mov_b64_e32 v[4:5], v[240:241]
	v_cvt_pk_f16_f32 v30, v30, v31
	v_lshl_add_u64 v[28:29], v[26:27], 4, s[2:3]
	v_cvt_pk_f16_f32 v1, v34, v35
	v_cvt_pk_f16_f32 v27, v36, v37
	v_cvt_pk_f16_f32 v31, v32, v33
	v_add_u32_e32 v1, 0x40004, v1
	v_add_u32_e32 v27, 0x40004, v27
	v_add_u32_e32 v32, 0x40004, v30
	v_add_u32_e32 v33, 0x40004, v31
	s_mov_b32 s2, 0x60000
	v_and_b32_e32 v30, 0xfff8fff8, v1
	v_and_b32_e32 v31, 0xfff8fff8, v27
	v_and_b32_e32 v32, 0xfff8fff8, v32
	v_and_b32_e32 v33, 0xfff8fff8, v33
	v_cmp_gt_u32_e32 vcc, s2, v26
	global_store_dwordx4 v[28:29], v[30:33], off
	s_and_saveexec_b64 s[2:3], vcc
	s_cbranch_execz .LBB0_654
	v_cvt_pk_f16_f32 v1, v18, v19
	v_add_u32_e32 v1, 0x40004, v1
	v_and_b32_e32 v18, 0xfff8fff8, v1
	v_cvt_pk_f16_f32 v1, v20, v21
	v_add_u32_e32 v1, 0x40004, v1
	v_and_b32_e32 v19, 0xfff8fff8, v1
	v_cvt_pk_f16_f32 v1, v10, v11
	v_add_u32_e32 v1, 0x40004, v1
	v_and_b32_e32 v20, 0xfff8fff8, v1
	v_cvt_pk_f16_f32 v1, v12, v13
	v_add_u32_e32 v1, 0x40004, v1
	v_add_co_u32_e32 v10, vcc, 0x200000, v28
	v_and_b32_e32 v21, 0xfff8fff8, v1
	s_nop 0
	v_addc_co_u32_e32 v11, vcc, 0, v29, vcc
	global_store_dwordx4 v[10:11], v[18:21], off
.LBB0_654:
	s_or_b64 exec, exec, s[2:3]
	s_mov_b32 s2, 0x40000
	v_cmp_gt_u32_e32 vcc, s2, v26
	s_and_saveexec_b64 s[2:3], vcc
	s_cbranch_execz .LBB0_656
	v_cvt_pk_f16_f32 v1, v22, v23
	v_add_u32_e32 v1, 0x40004, v1
	v_and_b32_e32 v10, 0xfff8fff8, v1
	v_cvt_pk_f16_f32 v1, v24, v25
	v_add_u32_e32 v1, 0x40004, v1
	v_and_b32_e32 v11, 0xfff8fff8, v1
	v_cvt_pk_f16_f32 v1, v14, v15
	v_add_u32_e32 v1, 0x40004, v1
	v_and_b32_e32 v12, 0xfff8fff8, v1
	v_cvt_pk_f16_f32 v1, v16, v17
	v_add_u32_e32 v1, 0x40004, v1
	v_add_co_u32_e32 v14, vcc, 0x400000, v28
	v_and_b32_e32 v13, 0xfff8fff8, v1
	s_nop 0
	v_addc_co_u32_e32 v15, vcc, 0, v29, vcc
	global_store_dwordx4 v[14:15], v[10:13], off
.LBB0_656:
	s_or_b64 exec, exec, s[2:3]
	s_mov_b32 s2, 0x20000
	v_cmp_gt_u32_e32 vcc, s2, v26
	s_and_b64 exec, exec, vcc
	s_cbranch_execz .LBB0_658
	v_cvt_pk_f16_f32 v1, v6, v7
	v_add_u32_e32 v1, 0x40004, v1
	v_and_b32_e32 v6, 0xfff8fff8, v1
	v_cvt_pk_f16_f32 v1, v8, v9
	v_add_u32_e32 v1, 0x40004, v1
	v_and_b32_e32 v7, 0xfff8fff8, v1
	v_cvt_pk_f16_f32 v1, v2, v3
	v_add_u32_e32 v1, 0x40004, v1
	v_and_b32_e32 v8, 0xfff8fff8, v1
	v_cvt_pk_f16_f32 v1, v4, v5
	v_add_u32_e32 v1, 0x40004, v1
	v_add_co_u32_e32 v2, vcc, 0x600000, v28
	v_and_b32_e32 v9, 0xfff8fff8, v1
	s_nop 0
	v_addc_co_u32_e32 v3, vcc, 0, v29, vcc
	global_store_dwordx4 v[2:3], v[6:9], off
